# K loops: snake order inside each group of 8 MFMAs so every MFMA shares its A or B operand with the previous one
# baseline (speedup 1.0000x reference)
.Lsp_p1:
.LBB0_277:
	ds_read_b128 v[148:151], v145
	ds_read_b128 v[152:155], v145 offset:1024
	ds_read_b128 v[156:159], v145 offset:2048
	ds_read_b128 v[160:163], v145 offset:3072
	ds_read_b128 v[166:169], v146
	ds_read_b128 v[170:173], v146 offset:1024
	ds_read_b128 v[174:177], v146 offset:2048
	ds_read_b128 v[178:181], v146 offset:3072
	s_add_u32 s28, s26, 0xfff80080
	s_addc_u32 s29, s27, -1
	s_cmp_eq_u32 s50, 28
	s_cselect_b32 s31, s2, s29
	s_cselect_b32 s30, s13, s28
	s_cselect_b32 s29, s15, s33
	s_cselect_b32 s28, s23, s25
	v_lshl_add_u64 v[214:215], s[26:27], 0, v[138:139]
	s_add_i32 m0, s37, 0xc000
	ds_read_b128 v[182:185], v147
	ds_read_b128 v[186:189], v147 offset:1024
	ds_read_b128 v[190:193], v147 offset:2048
	ds_read_b128 v[194:197], v147 offset:3072
	ds_read_b128 v[198:201], v147 offset:4096
	ds_read_b128 v[202:205], v147 offset:5120
	ds_read_b128 v[206:209], v147 offset:6144
	ds_read_b128 v[210:213], v147 offset:7168
	global_load_lds_dwordx4 v[214:215], off
	v_lshl_add_u64 v[214:215], s[26:27], 0, v[140:141]
	s_add_i32 m0, s37, 0xe000
	s_nop 0
	global_load_lds_dwordx4 v[214:215], off
	s_waitcnt vmcnt(8)
	s_waitcnt lgkmcnt(0)
	s_barrier
	v_mfma_f32_16x16x32_bf16 v[126:129], v[148:151], v[182:185], v[126:129]
	v_mfma_f32_16x16x32_bf16 v[122:125], v[156:159], v[182:185], v[122:125]
	v_mfma_f32_16x16x32_bf16 v[106:109], v[156:159], v[190:193], v[106:109]
	v_mfma_f32_16x16x32_bf16 v[110:113], v[148:151], v[190:193], v[110:113]
	v_mfma_f32_16x16x32_bf16 v[94:97], v[148:151], v[198:201], v[94:97]
	v_mfma_f32_16x16x32_bf16 v[90:93], v[156:159], v[198:201], v[90:93]
	v_mfma_f32_16x16x32_bf16 v[74:77], v[156:159], v[206:209], v[74:77]
	v_mfma_f32_16x16x32_bf16 v[78:81], v[148:151], v[206:209], v[78:81]
	v_mfma_f32_16x16x32_bf16 v[126:129], v[152:155], v[186:189], v[126:129]
	v_mfma_f32_16x16x32_bf16 v[122:125], v[160:163], v[186:189], v[122:125]
	v_mfma_f32_16x16x32_bf16 v[106:109], v[160:163], v[194:197], v[106:109]
	v_mfma_f32_16x16x32_bf16 v[110:113], v[152:155], v[194:197], v[110:113]
	v_mfma_f32_16x16x32_bf16 v[94:97], v[152:155], v[202:205], v[94:97]
	v_mfma_f32_16x16x32_bf16 v[90:93], v[160:163], v[202:205], v[90:93]
	v_mfma_f32_16x16x32_bf16 v[74:77], v[160:163], v[210:213], v[74:77]
	v_mfma_f32_16x16x32_bf16 v[78:81], v[152:155], v[210:213], v[78:81]
	v_mfma_f32_16x16x32_bf16 v[118:121], v[166:169], v[182:185], v[118:121]
	v_mfma_f32_16x16x32_bf16 v[114:117], v[174:177], v[182:185], v[114:117]
	v_mfma_f32_16x16x32_bf16 v[98:101], v[174:177], v[190:193], v[98:101]
	v_mfma_f32_16x16x32_bf16 v[102:105], v[166:169], v[190:193], v[102:105]
	v_mfma_f32_16x16x32_bf16 v[86:89], v[166:169], v[198:201], v[86:89]
	v_mfma_f32_16x16x32_bf16 v[82:85], v[174:177], v[198:201], v[82:85]
	v_mfma_f32_16x16x32_bf16 v[66:69], v[174:177], v[206:209], v[66:69]
	v_mfma_f32_16x16x32_bf16 v[70:73], v[166:169], v[206:209], v[70:73]
	v_mfma_f32_16x16x32_bf16 v[118:121], v[170:173], v[186:189], v[118:121]
	v_mfma_f32_16x16x32_bf16 v[114:117], v[178:181], v[186:189], v[114:117]
	v_mfma_f32_16x16x32_bf16 v[98:101], v[178:181], v[194:197], v[98:101]
	v_mfma_f32_16x16x32_bf16 v[102:105], v[170:173], v[194:197], v[102:105]
	v_mfma_f32_16x16x32_bf16 v[86:89], v[170:173], v[202:205], v[86:89]
	v_mfma_f32_16x16x32_bf16 v[82:85], v[178:181], v[202:205], v[82:85]
	v_mfma_f32_16x16x32_bf16 v[66:69], v[178:181], v[210:213], v[66:69]
	v_mfma_f32_16x16x32_bf16 v[70:73], v[170:173], v[210:213], v[70:73]
	s_barrier
	s_add_i32 s51, s48, s36
	v_lshl_add_u64 v[214:215], s[28:29], 0, v[132:133]
	s_mov_b32 m0, s51
	ds_read_b128 v[182:185], v147 offset:16384
	ds_read_b128 v[186:189], v147 offset:17408
	ds_read_b128 v[190:193], v147 offset:18432
	ds_read_b128 v[194:197], v147 offset:19456
	ds_read_b128 v[198:201], v147 offset:20480
	ds_read_b128 v[202:205], v147 offset:21504
	ds_read_b128 v[206:209], v147 offset:22528
	ds_read_b128 v[210:213], v147 offset:23552
	global_load_lds_dwordx4 v[214:215], off
	s_add_i32 m0, s51, 0x2000
	s_add_u32 s52, s28, 0x80000
	v_lshl_add_u64 v[216:217], s[28:29], 0, v[136:137]
	s_addc_u32 s53, s29, 0
	s_add_i32 s51, s49, s36
	global_load_lds_dwordx4 v[216:217], off
	v_lshl_add_u64 v[218:219], s[52:53], 0, v[132:133]
	s_mov_b32 m0, s51
	v_lshl_add_u64 v[220:221], s[30:31], 0, v[134:135]
	global_load_lds_dwordx4 v[218:219], off
	v_lshl_add_u64 v[218:219], s[52:53], 0, v[136:137]
	s_add_i32 m0, s51, 0x2000
	s_nop 0
	global_load_lds_dwordx4 v[218:219], off
	v_lshl_add_u64 v[218:219], s[30:31], 0, v[130:131]
	s_mov_b32 m0, s37
	s_nop 0
	global_load_lds_dwordx4 v[218:219], off
	s_mov_b32 m0, s38
	s_nop 0
	global_load_lds_dwordx4 v[220:221], off
	s_waitcnt vmcnt(8)
	s_waitcnt lgkmcnt(0)
	s_barrier
	v_mfma_f32_16x16x32_bf16 v[62:65], v[148:151], v[182:185], v[62:65]
	v_mfma_f32_16x16x32_bf16 v[58:61], v[156:159], v[182:185], v[58:61]
	v_mfma_f32_16x16x32_bf16 v[42:45], v[156:159], v[190:193], v[42:45]
	v_mfma_f32_16x16x32_bf16 v[46:49], v[148:151], v[190:193], v[46:49]
	v_mfma_f32_16x16x32_bf16 v[30:33], v[148:151], v[198:201], v[30:33]
	v_mfma_f32_16x16x32_bf16 v[26:29], v[156:159], v[198:201], v[26:29]
	v_mfma_f32_16x16x32_bf16 v[10:13], v[156:159], v[206:209], v[10:13]
	v_mfma_f32_16x16x32_bf16 v[14:17], v[148:151], v[206:209], v[14:17]
	v_mfma_f32_16x16x32_bf16 v[62:65], v[152:155], v[186:189], v[62:65]
	v_mfma_f32_16x16x32_bf16 v[58:61], v[160:163], v[186:189], v[58:61]
	v_mfma_f32_16x16x32_bf16 v[42:45], v[160:163], v[194:197], v[42:45]
	v_mfma_f32_16x16x32_bf16 v[46:49], v[152:155], v[194:197], v[46:49]
	v_mfma_f32_16x16x32_bf16 v[30:33], v[152:155], v[202:205], v[30:33]
	v_mfma_f32_16x16x32_bf16 v[26:29], v[160:163], v[202:205], v[26:29]
	v_mfma_f32_16x16x32_bf16 v[10:13], v[160:163], v[210:213], v[10:13]
	v_mfma_f32_16x16x32_bf16 v[14:17], v[152:155], v[210:213], v[14:17]
	v_mfma_f32_16x16x32_bf16 v[54:57], v[166:169], v[182:185], v[54:57]
	v_mfma_f32_16x16x32_bf16 v[50:53], v[174:177], v[182:185], v[50:53]
	v_mfma_f32_16x16x32_bf16 v[34:37], v[174:177], v[190:193], v[34:37]
	v_mfma_f32_16x16x32_bf16 v[38:41], v[166:169], v[190:193], v[38:41]
	v_mfma_f32_16x16x32_bf16 v[22:25], v[166:169], v[198:201], v[22:25]
	v_mfma_f32_16x16x32_bf16 v[18:21], v[174:177], v[198:201], v[18:21]
	v_mfma_f32_16x16x32_bf16 v[2:5], v[174:177], v[206:209], v[2:5]
	v_mfma_f32_16x16x32_bf16 v[6:9], v[166:169], v[206:209], v[6:9]
	v_mfma_f32_16x16x32_bf16 v[54:57], v[170:173], v[186:189], v[54:57]
	v_mfma_f32_16x16x32_bf16 v[50:53], v[178:181], v[186:189], v[50:53]
	v_mfma_f32_16x16x32_bf16 v[34:37], v[178:181], v[194:197], v[34:37]
	v_mfma_f32_16x16x32_bf16 v[38:41], v[170:173], v[194:197], v[38:41]
	v_mfma_f32_16x16x32_bf16 v[22:25], v[170:173], v[202:205], v[22:25]
	v_mfma_f32_16x16x32_bf16 v[18:21], v[178:181], v[202:205], v[18:21]
	v_mfma_f32_16x16x32_bf16 v[2:5], v[178:181], v[210:213], v[2:5]
	v_mfma_f32_16x16x32_bf16 v[6:9], v[170:173], v[210:213], v[6:9]
	s_barrier
	s_add_i32 s51, 0, 0x18000
	s_add_i32 s52, 0, 0x1c000
	v_add_u32_e32 v160, s51, v144
	v_add_u32_e32 v164, s52, v144
	ds_read_b128 v[148:151], v160
	ds_read_b128 v[152:155], v160 offset:1024
	ds_read_b128 v[156:159], v160 offset:2048
	ds_read_b128 v[160:163], v160 offset:3072
	ds_read_b128 v[166:169], v164
	ds_read_b128 v[170:173], v164 offset:1024
	ds_read_b128 v[174:177], v164 offset:2048
	ds_read_b128 v[178:181], v164 offset:3072
	s_add_u32 s30, s30, 0x80000
	s_addc_u32 s31, s31, 0
	s_mov_b32 m0, s39
	v_lshl_add_u64 v[222:223], s[30:31], 0, v[130:131]
	ds_read_b128 v[182:185], v147 offset:32768
	ds_read_b128 v[186:189], v147 offset:33792
	ds_read_b128 v[190:193], v147 offset:34816
	ds_read_b128 v[194:197], v147 offset:35840
	ds_read_b128 v[198:201], v147 offset:36864
	ds_read_b128 v[202:205], v147 offset:37888
	ds_read_b128 v[206:209], v147 offset:38912
	ds_read_b128 v[210:213], v147 offset:39936
	global_load_lds_dwordx4 v[222:223], off
	v_lshl_add_u64 v[222:223], s[30:31], 0, v[134:135]
	s_mov_b32 m0, s40
	s_nop 0
	global_load_lds_dwordx4 v[222:223], off
	s_waitcnt vmcnt(8)
	s_waitcnt lgkmcnt(0)
	s_barrier
	v_mfma_f32_16x16x32_bf16 v[126:129], v[148:151], v[182:185], v[126:129]
	v_mfma_f32_16x16x32_bf16 v[122:125], v[156:159], v[182:185], v[122:125]
	v_mfma_f32_16x16x32_bf16 v[106:109], v[156:159], v[190:193], v[106:109]
	v_mfma_f32_16x16x32_bf16 v[110:113], v[148:151], v[190:193], v[110:113]
	v_mfma_f32_16x16x32_bf16 v[94:97], v[148:151], v[198:201], v[94:97]
	v_mfma_f32_16x16x32_bf16 v[90:93], v[156:159], v[198:201], v[90:93]
	v_mfma_f32_16x16x32_bf16 v[74:77], v[156:159], v[206:209], v[74:77]
	v_mfma_f32_16x16x32_bf16 v[78:81], v[148:151], v[206:209], v[78:81]
	v_mfma_f32_16x16x32_bf16 v[126:129], v[152:155], v[186:189], v[126:129]
	v_mfma_f32_16x16x32_bf16 v[122:125], v[160:163], v[186:189], v[122:125]
	v_mfma_f32_16x16x32_bf16 v[106:109], v[160:163], v[194:197], v[106:109]
	v_mfma_f32_16x16x32_bf16 v[110:113], v[152:155], v[194:197], v[110:113]
	v_mfma_f32_16x16x32_bf16 v[94:97], v[152:155], v[202:205], v[94:97]
	v_mfma_f32_16x16x32_bf16 v[90:93], v[160:163], v[202:205], v[90:93]
	v_mfma_f32_16x16x32_bf16 v[74:77], v[160:163], v[210:213], v[74:77]
	v_mfma_f32_16x16x32_bf16 v[78:81], v[152:155], v[210:213], v[78:81]
	v_mfma_f32_16x16x32_bf16 v[118:121], v[166:169], v[182:185], v[118:121]
	v_mfma_f32_16x16x32_bf16 v[114:117], v[174:177], v[182:185], v[114:117]
	v_mfma_f32_16x16x32_bf16 v[98:101], v[174:177], v[190:193], v[98:101]
	v_mfma_f32_16x16x32_bf16 v[102:105], v[166:169], v[190:193], v[102:105]
	v_mfma_f32_16x16x32_bf16 v[86:89], v[166:169], v[198:201], v[86:89]
	v_mfma_f32_16x16x32_bf16 v[82:85], v[174:177], v[198:201], v[82:85]
	v_mfma_f32_16x16x32_bf16 v[66:69], v[174:177], v[206:209], v[66:69]
	v_mfma_f32_16x16x32_bf16 v[70:73], v[166:169], v[206:209], v[70:73]
	v_mfma_f32_16x16x32_bf16 v[118:121], v[170:173], v[186:189], v[118:121]
	v_mfma_f32_16x16x32_bf16 v[114:117], v[178:181], v[186:189], v[114:117]
	v_mfma_f32_16x16x32_bf16 v[98:101], v[178:181], v[194:197], v[98:101]
	v_mfma_f32_16x16x32_bf16 v[102:105], v[170:173], v[194:197], v[102:105]
	v_mfma_f32_16x16x32_bf16 v[86:89], v[170:173], v[202:205], v[86:89]
	v_mfma_f32_16x16x32_bf16 v[82:85], v[178:181], v[202:205], v[82:85]
	v_mfma_f32_16x16x32_bf16 v[66:69], v[178:181], v[210:213], v[66:69]
	v_mfma_f32_16x16x32_bf16 v[70:73], v[170:173], v[210:213], v[70:73]
	s_barrier
	s_add_i32 s30, s51, s36
	v_lshl_add_u64 v[214:215], v[214:215], 0, s[8:9]
	s_mov_b32 m0, s30
	ds_read_b128 v[182:185], v147 offset:49152
	ds_read_b128 v[186:189], v147 offset:50176
	ds_read_b128 v[190:193], v147 offset:51200
	ds_read_b128 v[194:197], v147 offset:52224
	ds_read_b128 v[198:201], v147 offset:53248
	ds_read_b128 v[202:205], v147 offset:54272
	ds_read_b128 v[206:209], v147 offset:55296
	ds_read_b128 v[210:213], v147 offset:56320
	global_load_lds_dwordx4 v[214:215], off
	s_add_i32 m0, s30, 0x2000
	s_add_u32 s28, s28, 0x80080
	v_lshl_add_u64 v[214:215], v[216:217], 0, s[8:9]
	s_addc_u32 s29, s29, 0
	s_add_i32 s30, s52, s36
	global_load_lds_dwordx4 v[214:215], off
	v_lshl_add_u64 v[214:215], s[28:29], 0, v[132:133]
	s_mov_b32 m0, s30
	s_nop 0
	global_load_lds_dwordx4 v[214:215], off
	v_lshl_add_u64 v[214:215], s[28:29], 0, v[136:137]
	s_add_i32 m0, s30, 0x2000
	s_nop 0
	global_load_lds_dwordx4 v[214:215], off
	v_lshl_add_u64 v[214:215], v[218:219], 0, s[8:9]
	s_mov_b32 m0, s44
	s_nop 0
	global_load_lds_dwordx4 v[214:215], off
	v_lshl_add_u64 v[214:215], v[220:221], 0, s[8:9]
	s_mov_b32 m0, s45
	s_nop 0
	global_load_lds_dwordx4 v[214:215], off
	s_waitcnt vmcnt(8)
	s_waitcnt lgkmcnt(0)
	s_barrier
	v_mfma_f32_16x16x32_bf16 v[62:65], v[148:151], v[182:185], v[62:65]
	v_mfma_f32_16x16x32_bf16 v[58:61], v[156:159], v[182:185], v[58:61]
	v_mfma_f32_16x16x32_bf16 v[42:45], v[156:159], v[190:193], v[42:45]
	v_mfma_f32_16x16x32_bf16 v[46:49], v[148:151], v[190:193], v[46:49]
	v_mfma_f32_16x16x32_bf16 v[30:33], v[148:151], v[198:201], v[30:33]
	v_mfma_f32_16x16x32_bf16 v[26:29], v[156:159], v[198:201], v[26:29]
	v_mfma_f32_16x16x32_bf16 v[10:13], v[156:159], v[206:209], v[10:13]
	v_mfma_f32_16x16x32_bf16 v[14:17], v[148:151], v[206:209], v[14:17]
	v_mfma_f32_16x16x32_bf16 v[62:65], v[152:155], v[186:189], v[62:65]
	v_mfma_f32_16x16x32_bf16 v[58:61], v[160:163], v[186:189], v[58:61]
	v_mfma_f32_16x16x32_bf16 v[42:45], v[160:163], v[194:197], v[42:45]
	v_mfma_f32_16x16x32_bf16 v[46:49], v[152:155], v[194:197], v[46:49]
	v_mfma_f32_16x16x32_bf16 v[30:33], v[152:155], v[202:205], v[30:33]
	v_mfma_f32_16x16x32_bf16 v[26:29], v[160:163], v[202:205], v[26:29]
	v_mfma_f32_16x16x32_bf16 v[10:13], v[160:163], v[210:213], v[10:13]
	v_mfma_f32_16x16x32_bf16 v[14:17], v[152:155], v[210:213], v[14:17]
	v_mfma_f32_16x16x32_bf16 v[54:57], v[166:169], v[182:185], v[54:57]
	v_mfma_f32_16x16x32_bf16 v[50:53], v[174:177], v[182:185], v[50:53]
	v_mfma_f32_16x16x32_bf16 v[34:37], v[174:177], v[190:193], v[34:37]
	v_mfma_f32_16x16x32_bf16 v[38:41], v[166:169], v[190:193], v[38:41]
	v_mfma_f32_16x16x32_bf16 v[22:25], v[166:169], v[198:201], v[22:25]
	v_mfma_f32_16x16x32_bf16 v[18:21], v[174:177], v[198:201], v[18:21]
	v_mfma_f32_16x16x32_bf16 v[2:5], v[174:177], v[206:209], v[2:5]
	v_mfma_f32_16x16x32_bf16 v[6:9], v[166:169], v[206:209], v[6:9]
	v_mfma_f32_16x16x32_bf16 v[54:57], v[170:173], v[186:189], v[54:57]
	v_mfma_f32_16x16x32_bf16 v[50:53], v[178:181], v[186:189], v[50:53]
	v_mfma_f32_16x16x32_bf16 v[34:37], v[178:181], v[194:197], v[34:37]
	v_mfma_f32_16x16x32_bf16 v[38:41], v[170:173], v[194:197], v[38:41]
	v_mfma_f32_16x16x32_bf16 v[22:25], v[170:173], v[202:205], v[22:25]
	v_mfma_f32_16x16x32_bf16 v[18:21], v[178:181], v[202:205], v[18:21]
	v_mfma_f32_16x16x32_bf16 v[2:5], v[178:181], v[210:213], v[2:5]
	v_mfma_f32_16x16x32_bf16 v[6:9], v[170:173], v[210:213], v[6:9]
	s_barrier
	s_add_i32 s50, s50, 2
	s_add_u32 s26, s26, 0x100
	s_addc_u32 s27, s27, 0
	s_add_u32 s25, s25, 0x100
	s_addc_u32 s33, s33, 0
	s_cmp_gt_u32 s50, 29
	s_cbranch_scc0 .LBB0_277
	s_setprio 0
	s_and_b64 vcc, exec, s[10:11]
	s_cbranch_vccz .LBB0_280
	s_barrier

.Lsp_p4:
.LBB0_704:
	ds_read_b128 v[144:147], v152
	ds_read_b128 v[156:159], v152 offset:1024
	ds_read_b128 v[160:163], v152 offset:2048
	ds_read_b128 v[166:169], v152 offset:3072
	ds_read_b128 v[170:173], v153
	ds_read_b128 v[174:177], v153 offset:1024
	ds_read_b128 v[178:181], v153 offset:2048
	ds_read_b128 v[182:185], v153 offset:3072
	s_add_u32 s24, s22, 0xfff80080
	s_addc_u32 s25, s23, -1
	s_cmp_eq_u32 s45, 28
	s_cselect_b32 s27, s17, s25
	s_cselect_b32 s26, s16, s24
	s_cselect_b32 s25, s21, s15
	s_cselect_b32 s24, s20, s5
	s_mov_b32 m0, s42
	v_lshl_add_u64 v[218:219], s[22:23], 0, v[140:141]
	ds_read_b128 v[186:189], v154
	ds_read_b128 v[190:193], v154 offset:1024
	ds_read_b128 v[194:197], v154 offset:2048
	ds_read_b128 v[198:201], v154 offset:3072
	ds_read_b128 v[202:205], v154 offset:4096
	ds_read_b128 v[206:209], v154 offset:5120
	ds_read_b128 v[210:213], v154 offset:6144
	ds_read_b128 v[214:217], v154 offset:7168
	global_load_lds_dwordx4 v[218:219], off
	v_lshl_add_u64 v[218:219], s[22:23], 0, v[142:143]
	s_add_i32 m0, s30, 0xe000
	s_nop 0
	global_load_lds_dwordx4 v[218:219], off
	s_waitcnt vmcnt(8)
	s_waitcnt lgkmcnt(0)
	s_barrier
	v_mfma_f32_16x16x32_bf16 v[126:129], v[144:147], v[186:189], v[126:129]
	v_mfma_f32_16x16x32_bf16 v[122:125], v[160:163], v[186:189], v[122:125]
	v_mfma_f32_16x16x32_bf16 v[106:109], v[160:163], v[194:197], v[106:109]
	v_mfma_f32_16x16x32_bf16 v[110:113], v[144:147], v[194:197], v[110:113]
	v_mfma_f32_16x16x32_bf16 v[94:97], v[144:147], v[202:205], v[94:97]
	v_mfma_f32_16x16x32_bf16 v[90:93], v[160:163], v[202:205], v[90:93]
	v_mfma_f32_16x16x32_bf16 v[74:77], v[160:163], v[210:213], v[74:77]
	v_mfma_f32_16x16x32_bf16 v[78:81], v[144:147], v[210:213], v[78:81]
	v_mfma_f32_16x16x32_bf16 v[126:129], v[156:159], v[190:193], v[126:129]
	v_mfma_f32_16x16x32_bf16 v[122:125], v[166:169], v[190:193], v[122:125]
	v_mfma_f32_16x16x32_bf16 v[106:109], v[166:169], v[198:201], v[106:109]
	v_mfma_f32_16x16x32_bf16 v[110:113], v[156:159], v[198:201], v[110:113]
	v_mfma_f32_16x16x32_bf16 v[94:97], v[156:159], v[206:209], v[94:97]
	v_mfma_f32_16x16x32_bf16 v[90:93], v[166:169], v[206:209], v[90:93]
	v_mfma_f32_16x16x32_bf16 v[74:77], v[166:169], v[214:217], v[74:77]
	v_mfma_f32_16x16x32_bf16 v[78:81], v[156:159], v[214:217], v[78:81]
	v_mfma_f32_16x16x32_bf16 v[118:121], v[170:173], v[186:189], v[118:121]
	v_mfma_f32_16x16x32_bf16 v[114:117], v[178:181], v[186:189], v[114:117]
	v_mfma_f32_16x16x32_bf16 v[98:101], v[178:181], v[194:197], v[98:101]
	v_mfma_f32_16x16x32_bf16 v[102:105], v[170:173], v[194:197], v[102:105]
	v_mfma_f32_16x16x32_bf16 v[86:89], v[170:173], v[202:205], v[86:89]
	v_mfma_f32_16x16x32_bf16 v[82:85], v[178:181], v[202:205], v[82:85]
	v_mfma_f32_16x16x32_bf16 v[66:69], v[178:181], v[210:213], v[66:69]
	v_mfma_f32_16x16x32_bf16 v[70:73], v[170:173], v[210:213], v[70:73]
	v_mfma_f32_16x16x32_bf16 v[118:121], v[174:177], v[190:193], v[118:121]
	v_mfma_f32_16x16x32_bf16 v[114:117], v[182:185], v[190:193], v[114:117]
	v_mfma_f32_16x16x32_bf16 v[98:101], v[182:185], v[198:201], v[98:101]
	v_mfma_f32_16x16x32_bf16 v[102:105], v[174:177], v[198:201], v[102:105]
	v_mfma_f32_16x16x32_bf16 v[86:89], v[174:177], v[206:209], v[86:89]
	v_mfma_f32_16x16x32_bf16 v[82:85], v[182:185], v[206:209], v[82:85]
	v_mfma_f32_16x16x32_bf16 v[66:69], v[182:185], v[214:217], v[66:69]
	v_mfma_f32_16x16x32_bf16 v[70:73], v[174:177], v[214:217], v[70:73]
	s_barrier
	s_add_i32 s46, s40, s29
	v_lshl_add_u64 v[218:219], s[24:25], 0, v[134:135]
	s_mov_b32 m0, s46
	ds_read_b128 v[186:189], v154 offset:16384
	ds_read_b128 v[190:193], v154 offset:17408
	ds_read_b128 v[194:197], v154 offset:18432
	ds_read_b128 v[198:201], v154 offset:19456
	ds_read_b128 v[202:205], v154 offset:20480
	ds_read_b128 v[206:209], v154 offset:21504
	ds_read_b128 v[210:213], v154 offset:22528
	ds_read_b128 v[214:217], v154 offset:23552
	global_load_lds_dwordx4 v[218:219], off
	s_add_i32 m0, s46, 0x2000
	s_add_u32 s46, s24, 0x80000
	v_lshl_add_u64 v[220:221], s[24:25], 0, v[138:139]
	s_addc_u32 s47, s25, 0
	s_add_i32 s48, s41, s29
	global_load_lds_dwordx4 v[220:221], off
	v_lshl_add_u64 v[222:223], s[46:47], 0, v[134:135]
	s_mov_b32 m0, s48
	v_lshl_add_u64 v[224:225], s[26:27], 0, v[136:137]
	global_load_lds_dwordx4 v[222:223], off
	v_lshl_add_u64 v[222:223], s[46:47], 0, v[138:139]
	s_add_i32 m0, s48, 0x2000
	s_nop 0
	global_load_lds_dwordx4 v[222:223], off
	v_lshl_add_u64 v[222:223], s[26:27], 0, v[132:133]
	s_mov_b32 m0, s30
	s_nop 0
	global_load_lds_dwordx4 v[222:223], off
	s_mov_b32 m0, s31
	s_nop 0
	global_load_lds_dwordx4 v[224:225], off
	s_waitcnt vmcnt(8)
	s_waitcnt lgkmcnt(0)
	s_barrier
	v_mfma_f32_16x16x32_bf16 v[62:65], v[144:147], v[186:189], v[62:65]
	v_mfma_f32_16x16x32_bf16 v[58:61], v[160:163], v[186:189], v[58:61]
	v_mfma_f32_16x16x32_bf16 v[42:45], v[160:163], v[194:197], v[42:45]
	v_mfma_f32_16x16x32_bf16 v[46:49], v[144:147], v[194:197], v[46:49]
	v_mfma_f32_16x16x32_bf16 v[30:33], v[144:147], v[202:205], v[30:33]
	v_mfma_f32_16x16x32_bf16 v[26:29], v[160:163], v[202:205], v[26:29]
	v_mfma_f32_16x16x32_bf16 v[10:13], v[160:163], v[210:213], v[10:13]
	v_mfma_f32_16x16x32_bf16 v[14:17], v[144:147], v[210:213], v[14:17]
	v_mfma_f32_16x16x32_bf16 v[62:65], v[156:159], v[190:193], v[62:65]
	v_mfma_f32_16x16x32_bf16 v[58:61], v[166:169], v[190:193], v[58:61]
	v_mfma_f32_16x16x32_bf16 v[42:45], v[166:169], v[198:201], v[42:45]
	v_mfma_f32_16x16x32_bf16 v[46:49], v[156:159], v[198:201], v[46:49]
	v_mfma_f32_16x16x32_bf16 v[30:33], v[156:159], v[206:209], v[30:33]
	v_mfma_f32_16x16x32_bf16 v[26:29], v[166:169], v[206:209], v[26:29]
	v_mfma_f32_16x16x32_bf16 v[10:13], v[166:169], v[214:217], v[10:13]
	v_mfma_f32_16x16x32_bf16 v[14:17], v[156:159], v[214:217], v[14:17]
	v_mfma_f32_16x16x32_bf16 v[54:57], v[170:173], v[186:189], v[54:57]
	v_mfma_f32_16x16x32_bf16 v[50:53], v[178:181], v[186:189], v[50:53]
	v_mfma_f32_16x16x32_bf16 v[34:37], v[178:181], v[194:197], v[34:37]
	v_mfma_f32_16x16x32_bf16 v[38:41], v[170:173], v[194:197], v[38:41]
	v_mfma_f32_16x16x32_bf16 v[22:25], v[170:173], v[202:205], v[22:25]
	v_mfma_f32_16x16x32_bf16 v[18:21], v[178:181], v[202:205], v[18:21]
	v_mfma_f32_16x16x32_bf16 v[2:5], v[178:181], v[210:213], v[2:5]
	v_mfma_f32_16x16x32_bf16 v[6:9], v[170:173], v[210:213], v[6:9]
	v_mfma_f32_16x16x32_bf16 v[54:57], v[174:177], v[190:193], v[54:57]
	v_mfma_f32_16x16x32_bf16 v[50:53], v[182:185], v[190:193], v[50:53]
	v_mfma_f32_16x16x32_bf16 v[34:37], v[182:185], v[198:201], v[34:37]
	v_mfma_f32_16x16x32_bf16 v[38:41], v[174:177], v[198:201], v[38:41]
	v_mfma_f32_16x16x32_bf16 v[22:25], v[174:177], v[206:209], v[22:25]
	v_mfma_f32_16x16x32_bf16 v[18:21], v[182:185], v[206:209], v[18:21]
	v_mfma_f32_16x16x32_bf16 v[2:5], v[182:185], v[214:217], v[2:5]
	v_mfma_f32_16x16x32_bf16 v[6:9], v[174:177], v[214:217], v[6:9]
	s_barrier
	s_add_i32 s46, 0, 0x18000
	v_add_u32_e32 v155, s46, v1
	s_add_i32 s47, 0, 0x1c000
	ds_read_b128 v[144:147], v155
	ds_read_b128 v[156:159], v155 offset:1024
	ds_read_b128 v[160:163], v155 offset:2048
	ds_read_b128 v[166:169], v155 offset:3072
	v_add_u32_e32 v155, s47, v1
	ds_read_b128 v[170:173], v155
	ds_read_b128 v[174:177], v155 offset:1024
	ds_read_b128 v[178:181], v155 offset:2048
	ds_read_b128 v[182:185], v155 offset:3072
	s_add_u32 s26, s26, 0x80000
	s_addc_u32 s27, s27, 0
	s_mov_b32 m0, s33
	v_lshl_add_u64 v[226:227], s[26:27], 0, v[132:133]
	ds_read_b128 v[186:189], v154 offset:32768
	ds_read_b128 v[190:193], v154 offset:33792
	ds_read_b128 v[194:197], v154 offset:34816
	ds_read_b128 v[198:201], v154 offset:35840
	ds_read_b128 v[202:205], v154 offset:36864
	ds_read_b128 v[206:209], v154 offset:37888
	ds_read_b128 v[210:213], v154 offset:38912
	ds_read_b128 v[214:217], v154 offset:39936
	global_load_lds_dwordx4 v[226:227], off
	v_lshl_add_u64 v[226:227], s[26:27], 0, v[136:137]
	s_mov_b32 m0, s34
	s_nop 0
	global_load_lds_dwordx4 v[226:227], off
	s_waitcnt vmcnt(8)
	s_waitcnt lgkmcnt(0)
	s_barrier
	v_mfma_f32_16x16x32_bf16 v[126:129], v[144:147], v[186:189], v[126:129]
	v_mfma_f32_16x16x32_bf16 v[122:125], v[160:163], v[186:189], v[122:125]
	v_mfma_f32_16x16x32_bf16 v[106:109], v[160:163], v[194:197], v[106:109]
	v_mfma_f32_16x16x32_bf16 v[110:113], v[144:147], v[194:197], v[110:113]
	v_mfma_f32_16x16x32_bf16 v[94:97], v[144:147], v[202:205], v[94:97]
	v_mfma_f32_16x16x32_bf16 v[90:93], v[160:163], v[202:205], v[90:93]
	v_mfma_f32_16x16x32_bf16 v[74:77], v[160:163], v[210:213], v[74:77]
	v_mfma_f32_16x16x32_bf16 v[78:81], v[144:147], v[210:213], v[78:81]
	v_mfma_f32_16x16x32_bf16 v[126:129], v[156:159], v[190:193], v[126:129]
	v_mfma_f32_16x16x32_bf16 v[122:125], v[166:169], v[190:193], v[122:125]
	v_mfma_f32_16x16x32_bf16 v[106:109], v[166:169], v[198:201], v[106:109]
	v_mfma_f32_16x16x32_bf16 v[110:113], v[156:159], v[198:201], v[110:113]
	v_mfma_f32_16x16x32_bf16 v[94:97], v[156:159], v[206:209], v[94:97]
	v_mfma_f32_16x16x32_bf16 v[90:93], v[166:169], v[206:209], v[90:93]
	v_mfma_f32_16x16x32_bf16 v[74:77], v[166:169], v[214:217], v[74:77]
	v_mfma_f32_16x16x32_bf16 v[78:81], v[156:159], v[214:217], v[78:81]
	v_mfma_f32_16x16x32_bf16 v[118:121], v[170:173], v[186:189], v[118:121]
	v_mfma_f32_16x16x32_bf16 v[114:117], v[178:181], v[186:189], v[114:117]
	v_mfma_f32_16x16x32_bf16 v[98:101], v[178:181], v[194:197], v[98:101]
	v_mfma_f32_16x16x32_bf16 v[102:105], v[170:173], v[194:197], v[102:105]
	v_mfma_f32_16x16x32_bf16 v[86:89], v[170:173], v[202:205], v[86:89]
	v_mfma_f32_16x16x32_bf16 v[82:85], v[178:181], v[202:205], v[82:85]
	v_mfma_f32_16x16x32_bf16 v[66:69], v[178:181], v[210:213], v[66:69]
	v_mfma_f32_16x16x32_bf16 v[70:73], v[170:173], v[210:213], v[70:73]
	v_mfma_f32_16x16x32_bf16 v[118:121], v[174:177], v[190:193], v[118:121]
	v_mfma_f32_16x16x32_bf16 v[114:117], v[182:185], v[190:193], v[114:117]
	v_mfma_f32_16x16x32_bf16 v[98:101], v[182:185], v[198:201], v[98:101]
	v_mfma_f32_16x16x32_bf16 v[102:105], v[174:177], v[198:201], v[102:105]
	v_mfma_f32_16x16x32_bf16 v[86:89], v[174:177], v[206:209], v[86:89]
	v_mfma_f32_16x16x32_bf16 v[82:85], v[182:185], v[206:209], v[82:85]
	v_mfma_f32_16x16x32_bf16 v[66:69], v[182:185], v[214:217], v[66:69]
	v_mfma_f32_16x16x32_bf16 v[70:73], v[174:177], v[214:217], v[70:73]
	s_barrier
	s_add_i32 s26, s46, s29
	v_lshl_add_u64 v[218:219], v[218:219], 0, s[10:11]
	s_mov_b32 m0, s26
	ds_read_b128 v[186:189], v154 offset:49152
	ds_read_b128 v[190:193], v154 offset:50176
	ds_read_b128 v[194:197], v154 offset:51200
	ds_read_b128 v[198:201], v154 offset:52224
	ds_read_b128 v[202:205], v154 offset:53248
	ds_read_b128 v[206:209], v154 offset:54272
	ds_read_b128 v[210:213], v154 offset:55296
	ds_read_b128 v[214:217], v154 offset:56320
	global_load_lds_dwordx4 v[218:219], off
	s_add_i32 m0, s26, 0x2000
	s_add_u32 s24, s24, 0x80080
	v_lshl_add_u64 v[218:219], v[220:221], 0, s[10:11]
	s_addc_u32 s25, s25, 0
	s_add_i32 s26, s47, s29
	global_load_lds_dwordx4 v[218:219], off
	v_lshl_add_u64 v[218:219], s[24:25], 0, v[134:135]
	s_mov_b32 m0, s26
	s_nop 0
	global_load_lds_dwordx4 v[218:219], off
	v_lshl_add_u64 v[218:219], s[24:25], 0, v[138:139]
	s_add_i32 m0, s26, 0x2000
	s_nop 0
	global_load_lds_dwordx4 v[218:219], off
	v_lshl_add_u64 v[218:219], v[222:223], 0, s[10:11]
	s_mov_b32 m0, s38
	s_nop 0
	global_load_lds_dwordx4 v[218:219], off
	v_lshl_add_u64 v[218:219], v[224:225], 0, s[10:11]
	s_mov_b32 m0, s39
	s_nop 0
	global_load_lds_dwordx4 v[218:219], off
	s_waitcnt vmcnt(8)
	s_waitcnt lgkmcnt(0)
	s_barrier
	v_mfma_f32_16x16x32_bf16 v[62:65], v[144:147], v[186:189], v[62:65]
	v_mfma_f32_16x16x32_bf16 v[58:61], v[160:163], v[186:189], v[58:61]
	v_mfma_f32_16x16x32_bf16 v[42:45], v[160:163], v[194:197], v[42:45]
	v_mfma_f32_16x16x32_bf16 v[46:49], v[144:147], v[194:197], v[46:49]
	v_mfma_f32_16x16x32_bf16 v[30:33], v[144:147], v[202:205], v[30:33]
	v_mfma_f32_16x16x32_bf16 v[26:29], v[160:163], v[202:205], v[26:29]
	v_mfma_f32_16x16x32_bf16 v[10:13], v[160:163], v[210:213], v[10:13]
	v_mfma_f32_16x16x32_bf16 v[14:17], v[144:147], v[210:213], v[14:17]
	v_mfma_f32_16x16x32_bf16 v[62:65], v[156:159], v[190:193], v[62:65]
	v_mfma_f32_16x16x32_bf16 v[58:61], v[166:169], v[190:193], v[58:61]
	v_mfma_f32_16x16x32_bf16 v[42:45], v[166:169], v[198:201], v[42:45]
	v_mfma_f32_16x16x32_bf16 v[46:49], v[156:159], v[198:201], v[46:49]
	v_mfma_f32_16x16x32_bf16 v[30:33], v[156:159], v[206:209], v[30:33]
	v_mfma_f32_16x16x32_bf16 v[26:29], v[166:169], v[206:209], v[26:29]
	v_mfma_f32_16x16x32_bf16 v[10:13], v[166:169], v[214:217], v[10:13]
	v_mfma_f32_16x16x32_bf16 v[14:17], v[156:159], v[214:217], v[14:17]
	v_mfma_f32_16x16x32_bf16 v[54:57], v[170:173], v[186:189], v[54:57]
	v_mfma_f32_16x16x32_bf16 v[50:53], v[178:181], v[186:189], v[50:53]
	v_mfma_f32_16x16x32_bf16 v[34:37], v[178:181], v[194:197], v[34:37]
	v_mfma_f32_16x16x32_bf16 v[38:41], v[170:173], v[194:197], v[38:41]
	v_mfma_f32_16x16x32_bf16 v[22:25], v[170:173], v[202:205], v[22:25]
	v_mfma_f32_16x16x32_bf16 v[18:21], v[178:181], v[202:205], v[18:21]
	v_mfma_f32_16x16x32_bf16 v[2:5], v[178:181], v[210:213], v[2:5]
	v_mfma_f32_16x16x32_bf16 v[6:9], v[170:173], v[210:213], v[6:9]
	v_mfma_f32_16x16x32_bf16 v[54:57], v[174:177], v[190:193], v[54:57]
	v_mfma_f32_16x16x32_bf16 v[50:53], v[182:185], v[190:193], v[50:53]
	v_mfma_f32_16x16x32_bf16 v[34:37], v[182:185], v[198:201], v[34:37]
	v_mfma_f32_16x16x32_bf16 v[38:41], v[174:177], v[198:201], v[38:41]
	v_mfma_f32_16x16x32_bf16 v[22:25], v[174:177], v[206:209], v[22:25]
	v_mfma_f32_16x16x32_bf16 v[18:21], v[182:185], v[206:209], v[18:21]
	v_mfma_f32_16x16x32_bf16 v[2:5], v[182:185], v[214:217], v[2:5]
	v_mfma_f32_16x16x32_bf16 v[6:9], v[174:177], v[214:217], v[6:9]
	s_barrier
	s_add_i32 s45, s45, 2
	s_add_u32 s22, s22, 0x100
	s_addc_u32 s23, s23, 0
	s_add_u32 s5, s5, 0x100
	s_addc_u32 s15, s15, 0
	s_cmp_gt_u32 s45, 29
	s_cbranch_scc0 .LBB0_704
	s_setprio 0
	s_and_b64 vcc, exec, s[12:13]
	s_cbranch_vccz .LBB0_707
	s_barrier

.Lsp_p5:
.LBB0_842:
	v_add_u32_e32 v158, s36, v152
	v_add_u32_e32 v162, s37, v152
	ds_read_b128 v[142:145], v158
	ds_read_b128 v[146:149], v158 offset:1024
	ds_read_b128 v[154:157], v158 offset:2048
	ds_read_b128 v[158:161], v158 offset:3072
	ds_read_b128 v[166:169], v162
	ds_read_b128 v[170:173], v162 offset:1024
	ds_read_b128 v[174:177], v162 offset:2048
	ds_read_b128 v[178:181], v162 offset:3072
	s_add_i32 s49, s20, 2
	s_add_u32 s21, s4, 0xfffa0080
	s_addc_u32 s22, s5, -1
	s_cmp_eq_u32 s46, s20
	s_cselect_b32 s20, s16, s47
	s_cselect_b32 s23, s15, s22
	s_cselect_b32 s22, s14, s21
	s_cselect_b32 s21, s17, s48
	v_lshl_add_u64 v[162:163], s[4:5], 0, v[138:139]
	s_add_i32 m0, s26, 0xc000
	ds_read_b128 v[182:185], v153
	ds_read_b128 v[186:189], v153 offset:1024
	ds_read_b128 v[190:193], v153 offset:2048
	ds_read_b128 v[194:197], v153 offset:3072
	ds_read_b128 v[198:201], v153 offset:4096
	ds_read_b128 v[202:205], v153 offset:5120
	ds_read_b128 v[206:209], v153 offset:6144
	ds_read_b128 v[210:213], v153 offset:7168
	global_load_lds_dwordx4 v[162:163], off
	v_lshl_add_u64 v[162:163], s[4:5], 0, v[140:141]
	s_add_i32 m0, s26, 0xe000
	s_nop 0
	global_load_lds_dwordx4 v[162:163], off
	s_waitcnt vmcnt(8)
	s_waitcnt lgkmcnt(0)
	s_barrier
	v_mfma_f32_16x16x32_bf16 v[126:129], v[142:145], v[182:185], v[126:129]
	v_mfma_f32_16x16x32_bf16 v[122:125], v[154:157], v[182:185], v[122:125]
	v_mfma_f32_16x16x32_bf16 v[114:117], v[154:157], v[190:193], v[114:117]
	v_mfma_f32_16x16x32_bf16 v[118:121], v[142:145], v[190:193], v[118:121]
	v_mfma_f32_16x16x32_bf16 v[110:113], v[142:145], v[198:201], v[110:113]
	v_mfma_f32_16x16x32_bf16 v[106:109], v[154:157], v[198:201], v[106:109]
	v_mfma_f32_16x16x32_bf16 v[98:101], v[154:157], v[206:209], v[98:101]
	v_mfma_f32_16x16x32_bf16 v[102:105], v[142:145], v[206:209], v[102:105]
	v_mfma_f32_16x16x32_bf16 v[126:129], v[146:149], v[186:189], v[126:129]
	v_mfma_f32_16x16x32_bf16 v[122:125], v[158:161], v[186:189], v[122:125]
	v_mfma_f32_16x16x32_bf16 v[114:117], v[158:161], v[194:197], v[114:117]
	v_mfma_f32_16x16x32_bf16 v[118:121], v[146:149], v[194:197], v[118:121]
	v_mfma_f32_16x16x32_bf16 v[110:113], v[146:149], v[202:205], v[110:113]
	v_mfma_f32_16x16x32_bf16 v[106:109], v[158:161], v[202:205], v[106:109]
	v_mfma_f32_16x16x32_bf16 v[98:101], v[158:161], v[210:213], v[98:101]
	v_mfma_f32_16x16x32_bf16 v[102:105], v[146:149], v[210:213], v[102:105]
	v_mfma_f32_16x16x32_bf16 v[94:97], v[166:169], v[182:185], v[94:97]
	v_mfma_f32_16x16x32_bf16 v[90:93], v[174:177], v[182:185], v[90:93]
	v_mfma_f32_16x16x32_bf16 v[82:85], v[174:177], v[190:193], v[82:85]
	v_mfma_f32_16x16x32_bf16 v[86:89], v[166:169], v[190:193], v[86:89]
	v_mfma_f32_16x16x32_bf16 v[78:81], v[166:169], v[198:201], v[78:81]
	v_mfma_f32_16x16x32_bf16 v[74:77], v[174:177], v[198:201], v[74:77]
	v_mfma_f32_16x16x32_bf16 v[66:69], v[174:177], v[206:209], v[66:69]
	v_mfma_f32_16x16x32_bf16 v[70:73], v[166:169], v[206:209], v[70:73]
	v_mfma_f32_16x16x32_bf16 v[94:97], v[170:173], v[186:189], v[94:97]
	v_mfma_f32_16x16x32_bf16 v[90:93], v[178:181], v[186:189], v[90:93]
	v_mfma_f32_16x16x32_bf16 v[82:85], v[178:181], v[194:197], v[82:85]
	v_mfma_f32_16x16x32_bf16 v[86:89], v[170:173], v[194:197], v[86:89]
	v_mfma_f32_16x16x32_bf16 v[78:81], v[170:173], v[202:205], v[78:81]
	v_mfma_f32_16x16x32_bf16 v[74:77], v[178:181], v[202:205], v[74:77]
	v_mfma_f32_16x16x32_bf16 v[66:69], v[178:181], v[210:213], v[66:69]
	v_mfma_f32_16x16x32_bf16 v[70:73], v[170:173], v[210:213], v[70:73]
	s_barrier
	s_add_i32 s50, s36, s25
	v_lshl_add_u64 v[162:163], s[20:21], 0, v[132:133]
	s_mov_b32 m0, s50
	ds_read_b128 v[182:185], v153 offset:16384
	ds_read_b128 v[186:189], v153 offset:17408
	ds_read_b128 v[190:193], v153 offset:18432
	ds_read_b128 v[194:197], v153 offset:19456
	ds_read_b128 v[198:201], v153 offset:20480
	ds_read_b128 v[202:205], v153 offset:21504
	ds_read_b128 v[206:209], v153 offset:22528
	ds_read_b128 v[210:213], v153 offset:23552
	global_load_lds_dwordx4 v[162:163], off
	s_add_i32 m0, s50, 0x2000
	s_add_u32 s50, s20, 0x60000
	v_lshl_add_u64 v[214:215], s[20:21], 0, v[136:137]
	s_addc_u32 s51, s21, 0
	s_add_i32 s52, s37, s25
	global_load_lds_dwordx4 v[214:215], off
	v_lshl_add_u64 v[216:217], s[50:51], 0, v[132:133]
	s_mov_b32 m0, s52
	v_lshl_add_u64 v[218:219], s[22:23], 0, v[134:135]
	global_load_lds_dwordx4 v[216:217], off
	v_lshl_add_u64 v[216:217], s[50:51], 0, v[136:137]
	s_add_i32 m0, s52, 0x2000
	s_nop 0
	global_load_lds_dwordx4 v[216:217], off
	v_lshl_add_u64 v[216:217], s[22:23], 0, v[130:131]
	s_mov_b32 m0, s26
	s_nop 0
	global_load_lds_dwordx4 v[216:217], off
	s_mov_b32 m0, s27
	s_nop 0
	global_load_lds_dwordx4 v[218:219], off
	s_waitcnt vmcnt(8)
	s_waitcnt lgkmcnt(0)
	s_barrier
	v_mfma_f32_16x16x32_bf16 v[62:65], v[142:145], v[182:185], v[62:65]
	v_mfma_f32_16x16x32_bf16 v[58:61], v[154:157], v[182:185], v[58:61]
	v_mfma_f32_16x16x32_bf16 v[50:53], v[154:157], v[190:193], v[50:53]
	v_mfma_f32_16x16x32_bf16 v[54:57], v[142:145], v[190:193], v[54:57]
	v_mfma_f32_16x16x32_bf16 v[46:49], v[142:145], v[198:201], v[46:49]
	v_mfma_f32_16x16x32_bf16 v[42:45], v[154:157], v[198:201], v[42:45]
	v_mfma_f32_16x16x32_bf16 v[34:37], v[154:157], v[206:209], v[34:37]
	v_mfma_f32_16x16x32_bf16 v[38:41], v[142:145], v[206:209], v[38:41]
	v_mfma_f32_16x16x32_bf16 v[62:65], v[146:149], v[186:189], v[62:65]
	v_mfma_f32_16x16x32_bf16 v[58:61], v[158:161], v[186:189], v[58:61]
	v_mfma_f32_16x16x32_bf16 v[50:53], v[158:161], v[194:197], v[50:53]
	v_mfma_f32_16x16x32_bf16 v[54:57], v[146:149], v[194:197], v[54:57]
	v_mfma_f32_16x16x32_bf16 v[46:49], v[146:149], v[202:205], v[46:49]
	v_mfma_f32_16x16x32_bf16 v[42:45], v[158:161], v[202:205], v[42:45]
	v_mfma_f32_16x16x32_bf16 v[34:37], v[158:161], v[210:213], v[34:37]
	v_mfma_f32_16x16x32_bf16 v[38:41], v[146:149], v[210:213], v[38:41]
	v_mfma_f32_16x16x32_bf16 v[30:33], v[166:169], v[182:185], v[30:33]
	v_mfma_f32_16x16x32_bf16 v[26:29], v[174:177], v[182:185], v[26:29]
	v_mfma_f32_16x16x32_bf16 v[18:21], v[174:177], v[190:193], v[18:21]
	v_mfma_f32_16x16x32_bf16 v[22:25], v[166:169], v[190:193], v[22:25]
	v_mfma_f32_16x16x32_bf16 v[14:17], v[166:169], v[198:201], v[14:17]
	v_mfma_f32_16x16x32_bf16 v[10:13], v[174:177], v[198:201], v[10:13]
	v_mfma_f32_16x16x32_bf16 v[2:5], v[174:177], v[206:209], v[2:5]
	v_mfma_f32_16x16x32_bf16 v[6:9], v[166:169], v[206:209], v[6:9]
	v_mfma_f32_16x16x32_bf16 v[30:33], v[170:173], v[186:189], v[30:33]
	v_mfma_f32_16x16x32_bf16 v[26:29], v[178:181], v[186:189], v[26:29]
	v_mfma_f32_16x16x32_bf16 v[18:21], v[178:181], v[194:197], v[18:21]
	v_mfma_f32_16x16x32_bf16 v[22:25], v[170:173], v[194:197], v[22:25]
	v_mfma_f32_16x16x32_bf16 v[14:17], v[170:173], v[202:205], v[14:17]
	v_mfma_f32_16x16x32_bf16 v[10:13], v[178:181], v[202:205], v[10:13]
	v_mfma_f32_16x16x32_bf16 v[2:5], v[178:181], v[210:213], v[2:5]
	v_mfma_f32_16x16x32_bf16 v[6:9], v[170:173], v[210:213], v[6:9]
	s_barrier
	s_add_i32 s50, 0, 0x18000
	s_add_i32 s51, 0, 0x1c000
	v_add_u32_e32 v158, s50, v152
	v_add_u32_e32 v164, s51, v152
	ds_read_b128 v[142:145], v158
	ds_read_b128 v[146:149], v158 offset:1024
	ds_read_b128 v[154:157], v158 offset:2048
	ds_read_b128 v[158:161], v158 offset:3072
	ds_read_b128 v[166:169], v164
	ds_read_b128 v[170:173], v164 offset:1024
	ds_read_b128 v[174:177], v164 offset:2048
	ds_read_b128 v[178:181], v164 offset:3072
	s_add_u32 s22, s22, 0x60000
	s_addc_u32 s23, s23, 0
	s_mov_b32 m0, s28
	v_lshl_add_u64 v[220:221], s[22:23], 0, v[130:131]
	ds_read_b128 v[182:185], v153 offset:32768
	ds_read_b128 v[186:189], v153 offset:33792
	ds_read_b128 v[190:193], v153 offset:34816
	ds_read_b128 v[194:197], v153 offset:35840
	ds_read_b128 v[198:201], v153 offset:36864
	ds_read_b128 v[202:205], v153 offset:37888
	ds_read_b128 v[206:209], v153 offset:38912
	ds_read_b128 v[210:213], v153 offset:39936
	global_load_lds_dwordx4 v[220:221], off
	v_lshl_add_u64 v[220:221], s[22:23], 0, v[134:135]
	s_mov_b32 m0, s29
	s_nop 0
	global_load_lds_dwordx4 v[220:221], off
	s_waitcnt vmcnt(8)
	s_waitcnt lgkmcnt(0)
	s_barrier
	v_mfma_f32_16x16x32_bf16 v[126:129], v[142:145], v[182:185], v[126:129]
	v_mfma_f32_16x16x32_bf16 v[122:125], v[154:157], v[182:185], v[122:125]
	v_mfma_f32_16x16x32_bf16 v[114:117], v[154:157], v[190:193], v[114:117]
	v_mfma_f32_16x16x32_bf16 v[118:121], v[142:145], v[190:193], v[118:121]
	v_mfma_f32_16x16x32_bf16 v[110:113], v[142:145], v[198:201], v[110:113]
	v_mfma_f32_16x16x32_bf16 v[106:109], v[154:157], v[198:201], v[106:109]
	v_mfma_f32_16x16x32_bf16 v[98:101], v[154:157], v[206:209], v[98:101]
	v_mfma_f32_16x16x32_bf16 v[102:105], v[142:145], v[206:209], v[102:105]
	v_mfma_f32_16x16x32_bf16 v[126:129], v[146:149], v[186:189], v[126:129]
	v_mfma_f32_16x16x32_bf16 v[122:125], v[158:161], v[186:189], v[122:125]
	v_mfma_f32_16x16x32_bf16 v[114:117], v[158:161], v[194:197], v[114:117]
	v_mfma_f32_16x16x32_bf16 v[118:121], v[146:149], v[194:197], v[118:121]
	v_mfma_f32_16x16x32_bf16 v[110:113], v[146:149], v[202:205], v[110:113]
	v_mfma_f32_16x16x32_bf16 v[106:109], v[158:161], v[202:205], v[106:109]
	v_mfma_f32_16x16x32_bf16 v[98:101], v[158:161], v[210:213], v[98:101]
	v_mfma_f32_16x16x32_bf16 v[102:105], v[146:149], v[210:213], v[102:105]
	v_mfma_f32_16x16x32_bf16 v[94:97], v[166:169], v[182:185], v[94:97]
	v_mfma_f32_16x16x32_bf16 v[90:93], v[174:177], v[182:185], v[90:93]
	v_mfma_f32_16x16x32_bf16 v[82:85], v[174:177], v[190:193], v[82:85]
	v_mfma_f32_16x16x32_bf16 v[86:89], v[166:169], v[190:193], v[86:89]
	v_mfma_f32_16x16x32_bf16 v[78:81], v[166:169], v[198:201], v[78:81]
	v_mfma_f32_16x16x32_bf16 v[74:77], v[174:177], v[198:201], v[74:77]
	v_mfma_f32_16x16x32_bf16 v[66:69], v[174:177], v[206:209], v[66:69]
	v_mfma_f32_16x16x32_bf16 v[70:73], v[166:169], v[206:209], v[70:73]
	v_mfma_f32_16x16x32_bf16 v[94:97], v[170:173], v[186:189], v[94:97]
	v_mfma_f32_16x16x32_bf16 v[90:93], v[178:181], v[186:189], v[90:93]
	v_mfma_f32_16x16x32_bf16 v[82:85], v[178:181], v[194:197], v[82:85]
	v_mfma_f32_16x16x32_bf16 v[86:89], v[170:173], v[194:197], v[86:89]
	v_mfma_f32_16x16x32_bf16 v[78:81], v[170:173], v[202:205], v[78:81]
	v_mfma_f32_16x16x32_bf16 v[74:77], v[178:181], v[202:205], v[74:77]
	v_mfma_f32_16x16x32_bf16 v[66:69], v[178:181], v[210:213], v[66:69]
	v_mfma_f32_16x16x32_bf16 v[70:73], v[170:173], v[210:213], v[70:73]
	s_barrier
	s_add_i32 s22, s50, s25
	v_lshl_add_u64 v[162:163], v[162:163], 0, s[8:9]
	s_mov_b32 m0, s22
	ds_read_b128 v[182:185], v153 offset:49152
	ds_read_b128 v[186:189], v153 offset:50176
	ds_read_b128 v[190:193], v153 offset:51200
	ds_read_b128 v[194:197], v153 offset:52224
	ds_read_b128 v[198:201], v153 offset:53248
	ds_read_b128 v[202:205], v153 offset:54272
	ds_read_b128 v[206:209], v153 offset:55296
	ds_read_b128 v[210:213], v153 offset:56320
	global_load_lds_dwordx4 v[162:163], off
	s_add_i32 m0, s22, 0x2000
	s_add_u32 s20, s20, 0x60080
	v_lshl_add_u64 v[162:163], v[214:215], 0, s[8:9]
	s_addc_u32 s21, s21, 0
	s_add_i32 s22, s51, s25
	global_load_lds_dwordx4 v[162:163], off
	v_lshl_add_u64 v[162:163], s[20:21], 0, v[132:133]
	s_mov_b32 m0, s22
	s_nop 0
	global_load_lds_dwordx4 v[162:163], off
	v_lshl_add_u64 v[162:163], s[20:21], 0, v[136:137]
	s_add_i32 m0, s22, 0x2000
	s_nop 0
	global_load_lds_dwordx4 v[162:163], off
	v_lshl_add_u64 v[162:163], v[216:217], 0, s[8:9]
	s_mov_b32 m0, s34
	s_nop 0
	global_load_lds_dwordx4 v[162:163], off
	v_lshl_add_u64 v[162:163], v[218:219], 0, s[8:9]
	s_mov_b32 m0, s35
	s_nop 0
	global_load_lds_dwordx4 v[162:163], off
	s_waitcnt vmcnt(8)
	s_waitcnt lgkmcnt(0)
	s_barrier
	v_mfma_f32_16x16x32_bf16 v[62:65], v[142:145], v[182:185], v[62:65]
	v_mfma_f32_16x16x32_bf16 v[58:61], v[154:157], v[182:185], v[58:61]
	v_mfma_f32_16x16x32_bf16 v[50:53], v[154:157], v[190:193], v[50:53]
	v_mfma_f32_16x16x32_bf16 v[54:57], v[142:145], v[190:193], v[54:57]
	v_mfma_f32_16x16x32_bf16 v[46:49], v[142:145], v[198:201], v[46:49]
	v_mfma_f32_16x16x32_bf16 v[42:45], v[154:157], v[198:201], v[42:45]
	v_mfma_f32_16x16x32_bf16 v[34:37], v[154:157], v[206:209], v[34:37]
	v_mfma_f32_16x16x32_bf16 v[38:41], v[142:145], v[206:209], v[38:41]
	v_mfma_f32_16x16x32_bf16 v[62:65], v[146:149], v[186:189], v[62:65]
	v_mfma_f32_16x16x32_bf16 v[58:61], v[158:161], v[186:189], v[58:61]
	v_mfma_f32_16x16x32_bf16 v[50:53], v[158:161], v[194:197], v[50:53]
	v_mfma_f32_16x16x32_bf16 v[54:57], v[146:149], v[194:197], v[54:57]
	v_mfma_f32_16x16x32_bf16 v[46:49], v[146:149], v[202:205], v[46:49]
	v_mfma_f32_16x16x32_bf16 v[42:45], v[158:161], v[202:205], v[42:45]
	v_mfma_f32_16x16x32_bf16 v[34:37], v[158:161], v[210:213], v[34:37]
	v_mfma_f32_16x16x32_bf16 v[38:41], v[146:149], v[210:213], v[38:41]
	v_mfma_f32_16x16x32_bf16 v[30:33], v[166:169], v[182:185], v[30:33]
	v_mfma_f32_16x16x32_bf16 v[26:29], v[174:177], v[182:185], v[26:29]
	v_mfma_f32_16x16x32_bf16 v[18:21], v[174:177], v[190:193], v[18:21]
	v_mfma_f32_16x16x32_bf16 v[22:25], v[166:169], v[190:193], v[22:25]
	v_mfma_f32_16x16x32_bf16 v[14:17], v[166:169], v[198:201], v[14:17]
	v_mfma_f32_16x16x32_bf16 v[10:13], v[174:177], v[198:201], v[10:13]
	v_mfma_f32_16x16x32_bf16 v[2:5], v[174:177], v[206:209], v[2:5]
	v_mfma_f32_16x16x32_bf16 v[6:9], v[166:169], v[206:209], v[6:9]
	v_mfma_f32_16x16x32_bf16 v[30:33], v[170:173], v[186:189], v[30:33]
	v_mfma_f32_16x16x32_bf16 v[26:29], v[178:181], v[186:189], v[26:29]
	v_mfma_f32_16x16x32_bf16 v[18:21], v[178:181], v[194:197], v[18:21]
	v_mfma_f32_16x16x32_bf16 v[22:25], v[170:173], v[194:197], v[22:25]
	v_mfma_f32_16x16x32_bf16 v[14:17], v[170:173], v[202:205], v[14:17]
	v_mfma_f32_16x16x32_bf16 v[10:13], v[178:181], v[202:205], v[10:13]
	v_mfma_f32_16x16x32_bf16 v[2:5], v[178:181], v[210:213], v[2:5]
	v_mfma_f32_16x16x32_bf16 v[6:9], v[170:173], v[210:213], v[6:9]
	s_barrier
	s_add_u32 s4, s4, 0x100
	s_addc_u32 s5, s5, 0
	s_add_u32 s47, s47, 0x100
	s_addc_u32 s48, s48, 0
	s_cmp_ge_i32 s49, s45
	s_mov_b32 s20, s49
	s_cbranch_scc0 .LBB0_842
	s_setprio 0
	s_and_b64 vcc, exec, s[10:11]
	s_cbranch_vccz .LBB0_845
	s_barrier

.Lsp_p6:
.LBB0_1019:
	ds_read_b128 v[142:145], v149
	ds_read_b128 v[154:157], v149 offset:1024
	ds_read_b128 v[158:161], v149 offset:2048
	ds_read_b128 v[166:169], v149 offset:3072
	ds_read_b128 v[170:173], v150
	ds_read_b128 v[174:177], v150 offset:1024
	ds_read_b128 v[178:181], v150 offset:2048
	ds_read_b128 v[182:185], v150 offset:3072
	s_add_u32 s28, s26, 0xfff80080
	s_addc_u32 s29, s27, -1
	s_cmp_eq_u32 s49, 28
	s_cselect_b32 s31, s1, s29
	s_cselect_b32 s30, s15, s28
	s_cselect_b32 s29, s17, s48
	s_cselect_b32 s28, s46, s47
	v_lshl_add_u64 v[162:163], s[26:27], 0, v[138:139]
	s_add_i32 m0, s34, 0xc000
	ds_read_b128 v[186:189], v151
	ds_read_b128 v[190:193], v151 offset:1024
	ds_read_b128 v[194:197], v151 offset:2048
	ds_read_b128 v[198:201], v151 offset:3072
	ds_read_b128 v[202:205], v151 offset:4096
	ds_read_b128 v[206:209], v151 offset:5120
	ds_read_b128 v[210:213], v151 offset:6144
	ds_read_b128 v[214:217], v151 offset:7168
	global_load_lds_dwordx4 v[162:163], off
	v_lshl_add_u64 v[162:163], s[26:27], 0, v[140:141]
	s_add_i32 m0, s34, 0xe000
	s_nop 0
	global_load_lds_dwordx4 v[162:163], off
	s_waitcnt vmcnt(8)
	s_waitcnt lgkmcnt(0)
	s_barrier
	v_mfma_f32_16x16x32_bf16 v[126:129], v[142:145], v[186:189], v[126:129]
	v_mfma_f32_16x16x32_bf16 v[122:125], v[158:161], v[186:189], v[122:125]
	v_mfma_f32_16x16x32_bf16 v[106:109], v[158:161], v[194:197], v[106:109]
	v_mfma_f32_16x16x32_bf16 v[110:113], v[142:145], v[194:197], v[110:113]
	v_mfma_f32_16x16x32_bf16 v[94:97], v[142:145], v[202:205], v[94:97]
	v_mfma_f32_16x16x32_bf16 v[90:93], v[158:161], v[202:205], v[90:93]
	v_mfma_f32_16x16x32_bf16 v[74:77], v[158:161], v[210:213], v[74:77]
	v_mfma_f32_16x16x32_bf16 v[78:81], v[142:145], v[210:213], v[78:81]
	v_mfma_f32_16x16x32_bf16 v[126:129], v[154:157], v[190:193], v[126:129]
	v_mfma_f32_16x16x32_bf16 v[122:125], v[166:169], v[190:193], v[122:125]
	v_mfma_f32_16x16x32_bf16 v[106:109], v[166:169], v[198:201], v[106:109]
	v_mfma_f32_16x16x32_bf16 v[110:113], v[154:157], v[198:201], v[110:113]
	v_mfma_f32_16x16x32_bf16 v[94:97], v[154:157], v[206:209], v[94:97]
	v_mfma_f32_16x16x32_bf16 v[90:93], v[166:169], v[206:209], v[90:93]
	v_mfma_f32_16x16x32_bf16 v[74:77], v[166:169], v[214:217], v[74:77]
	v_mfma_f32_16x16x32_bf16 v[78:81], v[154:157], v[214:217], v[78:81]
	v_mfma_f32_16x16x32_bf16 v[118:121], v[170:173], v[186:189], v[118:121]
	v_mfma_f32_16x16x32_bf16 v[114:117], v[178:181], v[186:189], v[114:117]
	v_mfma_f32_16x16x32_bf16 v[98:101], v[178:181], v[194:197], v[98:101]
	v_mfma_f32_16x16x32_bf16 v[102:105], v[170:173], v[194:197], v[102:105]
	v_mfma_f32_16x16x32_bf16 v[86:89], v[170:173], v[202:205], v[86:89]
	v_mfma_f32_16x16x32_bf16 v[82:85], v[178:181], v[202:205], v[82:85]
	v_mfma_f32_16x16x32_bf16 v[66:69], v[178:181], v[210:213], v[66:69]
	v_mfma_f32_16x16x32_bf16 v[70:73], v[170:173], v[210:213], v[70:73]
	v_mfma_f32_16x16x32_bf16 v[118:121], v[174:177], v[190:193], v[118:121]
	v_mfma_f32_16x16x32_bf16 v[114:117], v[182:185], v[190:193], v[114:117]
	v_mfma_f32_16x16x32_bf16 v[98:101], v[182:185], v[198:201], v[98:101]
	v_mfma_f32_16x16x32_bf16 v[102:105], v[174:177], v[198:201], v[102:105]
	v_mfma_f32_16x16x32_bf16 v[86:89], v[174:177], v[206:209], v[86:89]
	v_mfma_f32_16x16x32_bf16 v[82:85], v[182:185], v[206:209], v[82:85]
	v_mfma_f32_16x16x32_bf16 v[66:69], v[182:185], v[214:217], v[66:69]
	v_mfma_f32_16x16x32_bf16 v[70:73], v[174:177], v[214:217], v[70:73]
	s_barrier
	s_add_i32 s50, s44, s25
	v_lshl_add_u64 v[162:163], s[28:29], 0, v[132:133]
	s_mov_b32 m0, s50
	ds_read_b128 v[186:189], v151 offset:16384
	ds_read_b128 v[190:193], v151 offset:17408
	ds_read_b128 v[194:197], v151 offset:18432
	ds_read_b128 v[198:201], v151 offset:19456
	ds_read_b128 v[202:205], v151 offset:20480
	ds_read_b128 v[206:209], v151 offset:21504
	ds_read_b128 v[210:213], v151 offset:22528
	ds_read_b128 v[214:217], v151 offset:23552
	global_load_lds_dwordx4 v[162:163], off
	s_add_i32 m0, s50, 0x2000
	s_add_u32 s50, s28, 0x80000
	v_lshl_add_u64 v[218:219], s[28:29], 0, v[136:137]
	s_addc_u32 s51, s29, 0
	s_add_i32 s52, s45, s25
	global_load_lds_dwordx4 v[218:219], off
	v_lshl_add_u64 v[220:221], s[50:51], 0, v[132:133]
	s_mov_b32 m0, s52
	v_lshl_add_u64 v[222:223], s[30:31], 0, v[134:135]
	global_load_lds_dwordx4 v[220:221], off
	v_lshl_add_u64 v[220:221], s[50:51], 0, v[136:137]
	s_add_i32 m0, s52, 0x2000
	s_nop 0
	global_load_lds_dwordx4 v[220:221], off
	v_lshl_add_u64 v[220:221], s[30:31], 0, v[130:131]
	s_mov_b32 m0, s34
	s_nop 0
	global_load_lds_dwordx4 v[220:221], off
	s_mov_b32 m0, s35
	s_nop 0
	global_load_lds_dwordx4 v[222:223], off
	s_waitcnt vmcnt(8)
	s_waitcnt lgkmcnt(0)
	s_barrier
	v_mfma_f32_16x16x32_bf16 v[62:65], v[142:145], v[186:189], v[62:65]
	v_mfma_f32_16x16x32_bf16 v[58:61], v[158:161], v[186:189], v[58:61]
	v_mfma_f32_16x16x32_bf16 v[42:45], v[158:161], v[194:197], v[42:45]
	v_mfma_f32_16x16x32_bf16 v[46:49], v[142:145], v[194:197], v[46:49]
	v_mfma_f32_16x16x32_bf16 v[30:33], v[142:145], v[202:205], v[30:33]
	v_mfma_f32_16x16x32_bf16 v[26:29], v[158:161], v[202:205], v[26:29]
	v_mfma_f32_16x16x32_bf16 v[10:13], v[158:161], v[210:213], v[10:13]
	v_mfma_f32_16x16x32_bf16 v[14:17], v[142:145], v[210:213], v[14:17]
	v_mfma_f32_16x16x32_bf16 v[62:65], v[154:157], v[190:193], v[62:65]
	v_mfma_f32_16x16x32_bf16 v[58:61], v[166:169], v[190:193], v[58:61]
	v_mfma_f32_16x16x32_bf16 v[42:45], v[166:169], v[198:201], v[42:45]
	v_mfma_f32_16x16x32_bf16 v[46:49], v[154:157], v[198:201], v[46:49]
	v_mfma_f32_16x16x32_bf16 v[30:33], v[154:157], v[206:209], v[30:33]
	v_mfma_f32_16x16x32_bf16 v[26:29], v[166:169], v[206:209], v[26:29]
	v_mfma_f32_16x16x32_bf16 v[10:13], v[166:169], v[214:217], v[10:13]
	v_mfma_f32_16x16x32_bf16 v[14:17], v[154:157], v[214:217], v[14:17]
	v_mfma_f32_16x16x32_bf16 v[54:57], v[170:173], v[186:189], v[54:57]
	v_mfma_f32_16x16x32_bf16 v[50:53], v[178:181], v[186:189], v[50:53]
	v_mfma_f32_16x16x32_bf16 v[34:37], v[178:181], v[194:197], v[34:37]
	v_mfma_f32_16x16x32_bf16 v[38:41], v[170:173], v[194:197], v[38:41]
	v_mfma_f32_16x16x32_bf16 v[22:25], v[170:173], v[202:205], v[22:25]
	v_mfma_f32_16x16x32_bf16 v[18:21], v[178:181], v[202:205], v[18:21]
	v_mfma_f32_16x16x32_bf16 v[2:5], v[178:181], v[210:213], v[2:5]
	v_mfma_f32_16x16x32_bf16 v[6:9], v[170:173], v[210:213], v[6:9]
	v_mfma_f32_16x16x32_bf16 v[54:57], v[174:177], v[190:193], v[54:57]
	v_mfma_f32_16x16x32_bf16 v[50:53], v[182:185], v[190:193], v[50:53]
	v_mfma_f32_16x16x32_bf16 v[34:37], v[182:185], v[198:201], v[34:37]
	v_mfma_f32_16x16x32_bf16 v[38:41], v[174:177], v[198:201], v[38:41]
	v_mfma_f32_16x16x32_bf16 v[22:25], v[174:177], v[206:209], v[22:25]
	v_mfma_f32_16x16x32_bf16 v[18:21], v[182:185], v[206:209], v[18:21]
	v_mfma_f32_16x16x32_bf16 v[2:5], v[182:185], v[214:217], v[2:5]
	v_mfma_f32_16x16x32_bf16 v[6:9], v[174:177], v[214:217], v[6:9]
	s_barrier
	s_add_i32 s50, 0, 0x18000
	v_add_u32_e32 v153, s50, v148
	s_add_i32 s51, 0, 0x1c000
	ds_read_b128 v[142:145], v153
	ds_read_b128 v[154:157], v153 offset:1024
	ds_read_b128 v[158:161], v153 offset:2048
	ds_read_b128 v[166:169], v153 offset:3072
	v_add_u32_e32 v153, s51, v148
	ds_read_b128 v[170:173], v153
	ds_read_b128 v[174:177], v153 offset:1024
	ds_read_b128 v[178:181], v153 offset:2048
	ds_read_b128 v[182:185], v153 offset:3072
	s_add_u32 s30, s30, 0x80000
	s_addc_u32 s31, s31, 0
	s_mov_b32 m0, s36
	v_lshl_add_u64 v[224:225], s[30:31], 0, v[130:131]
	ds_read_b128 v[186:189], v151 offset:32768
	ds_read_b128 v[190:193], v151 offset:33792
	ds_read_b128 v[194:197], v151 offset:34816
	ds_read_b128 v[198:201], v151 offset:35840
	ds_read_b128 v[202:205], v151 offset:36864
	ds_read_b128 v[206:209], v151 offset:37888
	ds_read_b128 v[210:213], v151 offset:38912
	ds_read_b128 v[214:217], v151 offset:39936
	global_load_lds_dwordx4 v[224:225], off
	v_lshl_add_u64 v[224:225], s[30:31], 0, v[134:135]
	s_mov_b32 m0, s37
	s_nop 0
	global_load_lds_dwordx4 v[224:225], off
	s_waitcnt vmcnt(8)
	s_waitcnt lgkmcnt(0)
	s_barrier
	v_mfma_f32_16x16x32_bf16 v[126:129], v[142:145], v[186:189], v[126:129]
	v_mfma_f32_16x16x32_bf16 v[122:125], v[158:161], v[186:189], v[122:125]
	v_mfma_f32_16x16x32_bf16 v[106:109], v[158:161], v[194:197], v[106:109]
	v_mfma_f32_16x16x32_bf16 v[110:113], v[142:145], v[194:197], v[110:113]
	v_mfma_f32_16x16x32_bf16 v[94:97], v[142:145], v[202:205], v[94:97]
	v_mfma_f32_16x16x32_bf16 v[90:93], v[158:161], v[202:205], v[90:93]
	v_mfma_f32_16x16x32_bf16 v[74:77], v[158:161], v[210:213], v[74:77]
	v_mfma_f32_16x16x32_bf16 v[78:81], v[142:145], v[210:213], v[78:81]
	v_mfma_f32_16x16x32_bf16 v[126:129], v[154:157], v[190:193], v[126:129]
	v_mfma_f32_16x16x32_bf16 v[122:125], v[166:169], v[190:193], v[122:125]
	v_mfma_f32_16x16x32_bf16 v[106:109], v[166:169], v[198:201], v[106:109]
	v_mfma_f32_16x16x32_bf16 v[110:113], v[154:157], v[198:201], v[110:113]
	v_mfma_f32_16x16x32_bf16 v[94:97], v[154:157], v[206:209], v[94:97]
	v_mfma_f32_16x16x32_bf16 v[90:93], v[166:169], v[206:209], v[90:93]
	v_mfma_f32_16x16x32_bf16 v[74:77], v[166:169], v[214:217], v[74:77]
	v_mfma_f32_16x16x32_bf16 v[78:81], v[154:157], v[214:217], v[78:81]
	v_mfma_f32_16x16x32_bf16 v[118:121], v[170:173], v[186:189], v[118:121]
	v_mfma_f32_16x16x32_bf16 v[114:117], v[178:181], v[186:189], v[114:117]
	v_mfma_f32_16x16x32_bf16 v[98:101], v[178:181], v[194:197], v[98:101]
	v_mfma_f32_16x16x32_bf16 v[102:105], v[170:173], v[194:197], v[102:105]
	v_mfma_f32_16x16x32_bf16 v[86:89], v[170:173], v[202:205], v[86:89]
	v_mfma_f32_16x16x32_bf16 v[82:85], v[178:181], v[202:205], v[82:85]
	v_mfma_f32_16x16x32_bf16 v[66:69], v[178:181], v[210:213], v[66:69]
	v_mfma_f32_16x16x32_bf16 v[70:73], v[170:173], v[210:213], v[70:73]
	v_mfma_f32_16x16x32_bf16 v[118:121], v[174:177], v[190:193], v[118:121]
	v_mfma_f32_16x16x32_bf16 v[114:117], v[182:185], v[190:193], v[114:117]
	v_mfma_f32_16x16x32_bf16 v[98:101], v[182:185], v[198:201], v[98:101]
	v_mfma_f32_16x16x32_bf16 v[102:105], v[174:177], v[198:201], v[102:105]
	v_mfma_f32_16x16x32_bf16 v[86:89], v[174:177], v[206:209], v[86:89]
	v_mfma_f32_16x16x32_bf16 v[82:85], v[182:185], v[206:209], v[82:85]
	v_mfma_f32_16x16x32_bf16 v[66:69], v[182:185], v[214:217], v[66:69]
	v_mfma_f32_16x16x32_bf16 v[70:73], v[174:177], v[214:217], v[70:73]
	s_barrier
	s_add_i32 s30, s50, s25
	v_lshl_add_u64 v[162:163], v[162:163], 0, s[8:9]
	s_mov_b32 m0, s30
	ds_read_b128 v[186:189], v151 offset:49152
	ds_read_b128 v[190:193], v151 offset:50176
	ds_read_b128 v[194:197], v151 offset:51200
	ds_read_b128 v[198:201], v151 offset:52224
	ds_read_b128 v[202:205], v151 offset:53248
	ds_read_b128 v[206:209], v151 offset:54272
	ds_read_b128 v[210:213], v151 offset:55296
	ds_read_b128 v[214:217], v151 offset:56320
	global_load_lds_dwordx4 v[162:163], off
	s_add_i32 m0, s30, 0x2000
	s_add_u32 s28, s28, 0x80080
	v_lshl_add_u64 v[162:163], v[218:219], 0, s[8:9]
	s_addc_u32 s29, s29, 0
	s_add_i32 s30, s51, s25
	global_load_lds_dwordx4 v[162:163], off
	v_lshl_add_u64 v[162:163], s[28:29], 0, v[132:133]
	s_mov_b32 m0, s30
	s_nop 0
	global_load_lds_dwordx4 v[162:163], off
	v_lshl_add_u64 v[162:163], s[28:29], 0, v[136:137]
	s_add_i32 m0, s30, 0x2000
	s_nop 0
	global_load_lds_dwordx4 v[162:163], off
	v_lshl_add_u64 v[162:163], v[220:221], 0, s[8:9]
	s_mov_b32 m0, s41
	s_nop 0
	global_load_lds_dwordx4 v[162:163], off
	v_lshl_add_u64 v[162:163], v[222:223], 0, s[8:9]
	s_mov_b32 m0, s42
	s_nop 0
	global_load_lds_dwordx4 v[162:163], off
	s_waitcnt vmcnt(8)
	s_waitcnt lgkmcnt(0)
	s_barrier
	v_mfma_f32_16x16x32_bf16 v[62:65], v[142:145], v[186:189], v[62:65]
	v_mfma_f32_16x16x32_bf16 v[58:61], v[158:161], v[186:189], v[58:61]
	v_mfma_f32_16x16x32_bf16 v[42:45], v[158:161], v[194:197], v[42:45]
	v_mfma_f32_16x16x32_bf16 v[46:49], v[142:145], v[194:197], v[46:49]
	v_mfma_f32_16x16x32_bf16 v[30:33], v[142:145], v[202:205], v[30:33]
	v_mfma_f32_16x16x32_bf16 v[26:29], v[158:161], v[202:205], v[26:29]
	v_mfma_f32_16x16x32_bf16 v[10:13], v[158:161], v[210:213], v[10:13]
	v_mfma_f32_16x16x32_bf16 v[14:17], v[142:145], v[210:213], v[14:17]
	v_mfma_f32_16x16x32_bf16 v[62:65], v[154:157], v[190:193], v[62:65]
	v_mfma_f32_16x16x32_bf16 v[58:61], v[166:169], v[190:193], v[58:61]
	v_mfma_f32_16x16x32_bf16 v[42:45], v[166:169], v[198:201], v[42:45]
	v_mfma_f32_16x16x32_bf16 v[46:49], v[154:157], v[198:201], v[46:49]
	v_mfma_f32_16x16x32_bf16 v[30:33], v[154:157], v[206:209], v[30:33]
	v_mfma_f32_16x16x32_bf16 v[26:29], v[166:169], v[206:209], v[26:29]
	v_mfma_f32_16x16x32_bf16 v[10:13], v[166:169], v[214:217], v[10:13]
	v_mfma_f32_16x16x32_bf16 v[14:17], v[154:157], v[214:217], v[14:17]
	v_mfma_f32_16x16x32_bf16 v[54:57], v[170:173], v[186:189], v[54:57]
	v_mfma_f32_16x16x32_bf16 v[50:53], v[178:181], v[186:189], v[50:53]
	v_mfma_f32_16x16x32_bf16 v[34:37], v[178:181], v[194:197], v[34:37]
	v_mfma_f32_16x16x32_bf16 v[38:41], v[170:173], v[194:197], v[38:41]
	v_mfma_f32_16x16x32_bf16 v[22:25], v[170:173], v[202:205], v[22:25]
	v_mfma_f32_16x16x32_bf16 v[18:21], v[178:181], v[202:205], v[18:21]
	v_mfma_f32_16x16x32_bf16 v[2:5], v[178:181], v[210:213], v[2:5]
	v_mfma_f32_16x16x32_bf16 v[6:9], v[170:173], v[210:213], v[6:9]
	v_mfma_f32_16x16x32_bf16 v[54:57], v[174:177], v[190:193], v[54:57]
	v_mfma_f32_16x16x32_bf16 v[50:53], v[182:185], v[190:193], v[50:53]
	v_mfma_f32_16x16x32_bf16 v[34:37], v[182:185], v[198:201], v[34:37]
	v_mfma_f32_16x16x32_bf16 v[38:41], v[174:177], v[198:201], v[38:41]
	v_mfma_f32_16x16x32_bf16 v[22:25], v[174:177], v[206:209], v[22:25]
	v_mfma_f32_16x16x32_bf16 v[18:21], v[182:185], v[206:209], v[18:21]
	v_mfma_f32_16x16x32_bf16 v[2:5], v[182:185], v[214:217], v[2:5]
	v_mfma_f32_16x16x32_bf16 v[6:9], v[174:177], v[214:217], v[6:9]
	s_barrier
	s_add_i32 s49, s49, 2
	s_add_u32 s26, s26, 0x100
	s_addc_u32 s27, s27, 0
	s_add_u32 s47, s47, 0x100
	s_addc_u32 s48, s48, 0
	s_cmp_gt_u32 s49, 29
	s_cbranch_scc0 .LBB0_1019
	s_setprio 0
	s_and_b64 vcc, exec, s[10:11]
	s_cbranch_vccz .LBB0_1022
	s_barrier

.Lsp_p9:
.LBB0_1220:
	ds_read_b128 v[142:145], v149
	ds_read_b128 v[154:157], v149 offset:1024
	ds_read_b128 v[158:161], v149 offset:2048
	ds_read_b128 v[166:169], v149 offset:3072
	ds_read_b128 v[170:173], v150
	ds_read_b128 v[174:177], v150 offset:1024
	ds_read_b128 v[178:181], v150 offset:2048
	ds_read_b128 v[182:185], v150 offset:3072
	s_add_u32 s30, s28, 0xfffe0080
	s_addc_u32 s31, s29, -1
	s_cmp_eq_u32 s51, 4
	s_cselect_b32 s35, s1, s31
	s_cselect_b32 s34, s17, s30
	s_cselect_b32 s31, s19, s50
	s_cselect_b32 s30, s48, s49
	v_lshl_add_u64 v[162:163], s[28:29], 0, v[138:139]
	s_add_i32 m0, s27, 0xc000
	ds_read_b128 v[186:189], v151
	ds_read_b128 v[190:193], v151 offset:1024
	ds_read_b128 v[194:197], v151 offset:2048
	ds_read_b128 v[198:201], v151 offset:3072
	ds_read_b128 v[202:205], v151 offset:4096
	ds_read_b128 v[206:209], v151 offset:5120
	ds_read_b128 v[210:213], v151 offset:6144
	ds_read_b128 v[214:217], v151 offset:7168
	global_load_lds_dwordx4 v[162:163], off
	v_lshl_add_u64 v[162:163], s[28:29], 0, v[140:141]
	s_add_i32 m0, s27, 0xe000
	s_nop 0
	global_load_lds_dwordx4 v[162:163], off
	s_waitcnt vmcnt(8)
	s_waitcnt lgkmcnt(0)
	s_barrier
	v_mfma_f32_16x16x32_bf16 v[126:129], v[142:145], v[186:189], v[126:129]
	v_mfma_f32_16x16x32_bf16 v[122:125], v[158:161], v[186:189], v[122:125]
	v_mfma_f32_16x16x32_bf16 v[106:109], v[158:161], v[194:197], v[106:109]
	v_mfma_f32_16x16x32_bf16 v[110:113], v[142:145], v[194:197], v[110:113]
	v_mfma_f32_16x16x32_bf16 v[94:97], v[142:145], v[202:205], v[94:97]
	v_mfma_f32_16x16x32_bf16 v[90:93], v[158:161], v[202:205], v[90:93]
	v_mfma_f32_16x16x32_bf16 v[74:77], v[158:161], v[210:213], v[74:77]
	v_mfma_f32_16x16x32_bf16 v[78:81], v[142:145], v[210:213], v[78:81]
	v_mfma_f32_16x16x32_bf16 v[126:129], v[154:157], v[190:193], v[126:129]
	v_mfma_f32_16x16x32_bf16 v[122:125], v[166:169], v[190:193], v[122:125]
	v_mfma_f32_16x16x32_bf16 v[106:109], v[166:169], v[198:201], v[106:109]
	v_mfma_f32_16x16x32_bf16 v[110:113], v[154:157], v[198:201], v[110:113]
	v_mfma_f32_16x16x32_bf16 v[94:97], v[154:157], v[206:209], v[94:97]
	v_mfma_f32_16x16x32_bf16 v[90:93], v[166:169], v[206:209], v[90:93]
	v_mfma_f32_16x16x32_bf16 v[74:77], v[166:169], v[214:217], v[74:77]
	v_mfma_f32_16x16x32_bf16 v[78:81], v[154:157], v[214:217], v[78:81]
	v_mfma_f32_16x16x32_bf16 v[118:121], v[170:173], v[186:189], v[118:121]
	v_mfma_f32_16x16x32_bf16 v[114:117], v[178:181], v[186:189], v[114:117]
	v_mfma_f32_16x16x32_bf16 v[98:101], v[178:181], v[194:197], v[98:101]
	v_mfma_f32_16x16x32_bf16 v[102:105], v[170:173], v[194:197], v[102:105]
	v_mfma_f32_16x16x32_bf16 v[86:89], v[170:173], v[202:205], v[86:89]
	v_mfma_f32_16x16x32_bf16 v[82:85], v[178:181], v[202:205], v[82:85]
	v_mfma_f32_16x16x32_bf16 v[66:69], v[178:181], v[210:213], v[66:69]
	v_mfma_f32_16x16x32_bf16 v[70:73], v[170:173], v[210:213], v[70:73]
	v_mfma_f32_16x16x32_bf16 v[118:121], v[174:177], v[190:193], v[118:121]
	v_mfma_f32_16x16x32_bf16 v[114:117], v[182:185], v[190:193], v[114:117]
	v_mfma_f32_16x16x32_bf16 v[98:101], v[182:185], v[198:201], v[98:101]
	v_mfma_f32_16x16x32_bf16 v[102:105], v[174:177], v[198:201], v[102:105]
	v_mfma_f32_16x16x32_bf16 v[86:89], v[174:177], v[206:209], v[86:89]
	v_mfma_f32_16x16x32_bf16 v[82:85], v[182:185], v[206:209], v[82:85]
	v_mfma_f32_16x16x32_bf16 v[66:69], v[182:185], v[214:217], v[66:69]
	v_mfma_f32_16x16x32_bf16 v[70:73], v[174:177], v[214:217], v[70:73]
	s_barrier
	s_add_i32 s52, s46, s2
	v_lshl_add_u64 v[162:163], s[30:31], 0, v[132:133]
	s_mov_b32 m0, s52
	ds_read_b128 v[186:189], v151 offset:16384
	ds_read_b128 v[190:193], v151 offset:17408
	ds_read_b128 v[194:197], v151 offset:18432
	ds_read_b128 v[198:201], v151 offset:19456
	ds_read_b128 v[202:205], v151 offset:20480
	ds_read_b128 v[206:209], v151 offset:21504
	ds_read_b128 v[210:213], v151 offset:22528
	ds_read_b128 v[214:217], v151 offset:23552
	global_load_lds_dwordx4 v[162:163], off
	s_add_i32 m0, s52, 0x2000
	s_add_u32 s52, s30, 0x20000
	v_lshl_add_u64 v[218:219], s[30:31], 0, v[136:137]
	s_addc_u32 s53, s31, 0
	s_add_i32 s54, s47, s2
	global_load_lds_dwordx4 v[218:219], off
	v_lshl_add_u64 v[220:221], s[52:53], 0, v[132:133]
	s_mov_b32 m0, s54
	v_lshl_add_u64 v[222:223], s[34:35], 0, v[134:135]
	global_load_lds_dwordx4 v[220:221], off
	v_lshl_add_u64 v[220:221], s[52:53], 0, v[136:137]
	s_add_i32 m0, s54, 0x2000
	s_nop 0
	global_load_lds_dwordx4 v[220:221], off
	v_lshl_add_u64 v[220:221], s[34:35], 0, v[130:131]
	s_mov_b32 m0, s27
	s_nop 0
	global_load_lds_dwordx4 v[220:221], off
	s_mov_b32 m0, s37
	s_nop 0
	global_load_lds_dwordx4 v[222:223], off
	s_waitcnt vmcnt(8)
	s_waitcnt lgkmcnt(0)
	s_barrier
	v_mfma_f32_16x16x32_bf16 v[62:65], v[142:145], v[186:189], v[62:65]
	v_mfma_f32_16x16x32_bf16 v[58:61], v[158:161], v[186:189], v[58:61]
	v_mfma_f32_16x16x32_bf16 v[42:45], v[158:161], v[194:197], v[42:45]
	v_mfma_f32_16x16x32_bf16 v[46:49], v[142:145], v[194:197], v[46:49]
	v_mfma_f32_16x16x32_bf16 v[30:33], v[142:145], v[202:205], v[30:33]
	v_mfma_f32_16x16x32_bf16 v[26:29], v[158:161], v[202:205], v[26:29]
	v_mfma_f32_16x16x32_bf16 v[10:13], v[158:161], v[210:213], v[10:13]
	v_mfma_f32_16x16x32_bf16 v[14:17], v[142:145], v[210:213], v[14:17]
	v_mfma_f32_16x16x32_bf16 v[62:65], v[154:157], v[190:193], v[62:65]
	v_mfma_f32_16x16x32_bf16 v[58:61], v[166:169], v[190:193], v[58:61]
	v_mfma_f32_16x16x32_bf16 v[42:45], v[166:169], v[198:201], v[42:45]
	v_mfma_f32_16x16x32_bf16 v[46:49], v[154:157], v[198:201], v[46:49]
	v_mfma_f32_16x16x32_bf16 v[30:33], v[154:157], v[206:209], v[30:33]
	v_mfma_f32_16x16x32_bf16 v[26:29], v[166:169], v[206:209], v[26:29]
	v_mfma_f32_16x16x32_bf16 v[10:13], v[166:169], v[214:217], v[10:13]
	v_mfma_f32_16x16x32_bf16 v[14:17], v[154:157], v[214:217], v[14:17]
	v_mfma_f32_16x16x32_bf16 v[54:57], v[170:173], v[186:189], v[54:57]
	v_mfma_f32_16x16x32_bf16 v[50:53], v[178:181], v[186:189], v[50:53]
	v_mfma_f32_16x16x32_bf16 v[34:37], v[178:181], v[194:197], v[34:37]
	v_mfma_f32_16x16x32_bf16 v[38:41], v[170:173], v[194:197], v[38:41]
	v_mfma_f32_16x16x32_bf16 v[22:25], v[170:173], v[202:205], v[22:25]
	v_mfma_f32_16x16x32_bf16 v[18:21], v[178:181], v[202:205], v[18:21]
	v_mfma_f32_16x16x32_bf16 v[2:5], v[178:181], v[210:213], v[2:5]
	v_mfma_f32_16x16x32_bf16 v[6:9], v[170:173], v[210:213], v[6:9]
	v_mfma_f32_16x16x32_bf16 v[54:57], v[174:177], v[190:193], v[54:57]
	v_mfma_f32_16x16x32_bf16 v[50:53], v[182:185], v[190:193], v[50:53]
	v_mfma_f32_16x16x32_bf16 v[34:37], v[182:185], v[198:201], v[34:37]
	v_mfma_f32_16x16x32_bf16 v[38:41], v[174:177], v[198:201], v[38:41]
	v_mfma_f32_16x16x32_bf16 v[22:25], v[174:177], v[206:209], v[22:25]
	v_mfma_f32_16x16x32_bf16 v[18:21], v[182:185], v[206:209], v[18:21]
	v_mfma_f32_16x16x32_bf16 v[2:5], v[182:185], v[214:217], v[2:5]
	v_mfma_f32_16x16x32_bf16 v[6:9], v[174:177], v[214:217], v[6:9]
	s_barrier
	s_add_i32 s52, 0, 0x18000
	v_add_u32_e32 v153, s52, v148
	s_add_i32 s53, 0, 0x1c000
	ds_read_b128 v[142:145], v153
	ds_read_b128 v[154:157], v153 offset:1024
	ds_read_b128 v[158:161], v153 offset:2048
	ds_read_b128 v[166:169], v153 offset:3072
	v_add_u32_e32 v153, s53, v148
	ds_read_b128 v[170:173], v153
	ds_read_b128 v[174:177], v153 offset:1024
	ds_read_b128 v[178:181], v153 offset:2048
	ds_read_b128 v[182:185], v153 offset:3072
	s_add_u32 s34, s34, 0x20000
	s_addc_u32 s35, s35, 0
	s_mov_b32 m0, s38
	v_lshl_add_u64 v[224:225], s[34:35], 0, v[130:131]
	ds_read_b128 v[186:189], v151 offset:32768
	ds_read_b128 v[190:193], v151 offset:33792
	ds_read_b128 v[194:197], v151 offset:34816
	ds_read_b128 v[198:201], v151 offset:35840
	ds_read_b128 v[202:205], v151 offset:36864
	ds_read_b128 v[206:209], v151 offset:37888
	ds_read_b128 v[210:213], v151 offset:38912
	ds_read_b128 v[214:217], v151 offset:39936
	global_load_lds_dwordx4 v[224:225], off
	v_lshl_add_u64 v[224:225], s[34:35], 0, v[134:135]
	s_mov_b32 m0, s39
	s_nop 0
	global_load_lds_dwordx4 v[224:225], off
	s_waitcnt vmcnt(8)
	s_waitcnt lgkmcnt(0)
	s_barrier
	v_mfma_f32_16x16x32_bf16 v[126:129], v[142:145], v[186:189], v[126:129]
	v_mfma_f32_16x16x32_bf16 v[122:125], v[158:161], v[186:189], v[122:125]
	v_mfma_f32_16x16x32_bf16 v[106:109], v[158:161], v[194:197], v[106:109]
	v_mfma_f32_16x16x32_bf16 v[110:113], v[142:145], v[194:197], v[110:113]
	v_mfma_f32_16x16x32_bf16 v[94:97], v[142:145], v[202:205], v[94:97]
	v_mfma_f32_16x16x32_bf16 v[90:93], v[158:161], v[202:205], v[90:93]
	v_mfma_f32_16x16x32_bf16 v[74:77], v[158:161], v[210:213], v[74:77]
	v_mfma_f32_16x16x32_bf16 v[78:81], v[142:145], v[210:213], v[78:81]
	v_mfma_f32_16x16x32_bf16 v[126:129], v[154:157], v[190:193], v[126:129]
	v_mfma_f32_16x16x32_bf16 v[122:125], v[166:169], v[190:193], v[122:125]
	v_mfma_f32_16x16x32_bf16 v[106:109], v[166:169], v[198:201], v[106:109]
	v_mfma_f32_16x16x32_bf16 v[110:113], v[154:157], v[198:201], v[110:113]
	v_mfma_f32_16x16x32_bf16 v[94:97], v[154:157], v[206:209], v[94:97]
	v_mfma_f32_16x16x32_bf16 v[90:93], v[166:169], v[206:209], v[90:93]
	v_mfma_f32_16x16x32_bf16 v[74:77], v[166:169], v[214:217], v[74:77]
	v_mfma_f32_16x16x32_bf16 v[78:81], v[154:157], v[214:217], v[78:81]
	v_mfma_f32_16x16x32_bf16 v[118:121], v[170:173], v[186:189], v[118:121]
	v_mfma_f32_16x16x32_bf16 v[114:117], v[178:181], v[186:189], v[114:117]
	v_mfma_f32_16x16x32_bf16 v[98:101], v[178:181], v[194:197], v[98:101]
	v_mfma_f32_16x16x32_bf16 v[102:105], v[170:173], v[194:197], v[102:105]
	v_mfma_f32_16x16x32_bf16 v[86:89], v[170:173], v[202:205], v[86:89]
	v_mfma_f32_16x16x32_bf16 v[82:85], v[178:181], v[202:205], v[82:85]
	v_mfma_f32_16x16x32_bf16 v[66:69], v[178:181], v[210:213], v[66:69]
	v_mfma_f32_16x16x32_bf16 v[70:73], v[170:173], v[210:213], v[70:73]
	v_mfma_f32_16x16x32_bf16 v[118:121], v[174:177], v[190:193], v[118:121]
	v_mfma_f32_16x16x32_bf16 v[114:117], v[182:185], v[190:193], v[114:117]
	v_mfma_f32_16x16x32_bf16 v[98:101], v[182:185], v[198:201], v[98:101]
	v_mfma_f32_16x16x32_bf16 v[102:105], v[174:177], v[198:201], v[102:105]
	v_mfma_f32_16x16x32_bf16 v[86:89], v[174:177], v[206:209], v[86:89]
	v_mfma_f32_16x16x32_bf16 v[82:85], v[182:185], v[206:209], v[82:85]
	v_mfma_f32_16x16x32_bf16 v[66:69], v[182:185], v[214:217], v[66:69]
	v_mfma_f32_16x16x32_bf16 v[70:73], v[174:177], v[214:217], v[70:73]
	s_barrier
	s_add_i32 s34, s52, s2
	v_lshl_add_u64 v[162:163], v[162:163], 0, s[10:11]
	s_mov_b32 m0, s34
	ds_read_b128 v[186:189], v151 offset:49152
	ds_read_b128 v[190:193], v151 offset:50176
	ds_read_b128 v[194:197], v151 offset:51200
	ds_read_b128 v[198:201], v151 offset:52224
	ds_read_b128 v[202:205], v151 offset:53248
	ds_read_b128 v[206:209], v151 offset:54272
	ds_read_b128 v[210:213], v151 offset:55296
	ds_read_b128 v[214:217], v151 offset:56320
	global_load_lds_dwordx4 v[162:163], off
	s_add_i32 m0, s34, 0x2000
	s_add_u32 s30, s30, 0x20080
	v_lshl_add_u64 v[162:163], v[218:219], 0, s[10:11]
	s_addc_u32 s31, s31, 0
	s_add_i32 s34, s53, s2
	global_load_lds_dwordx4 v[162:163], off
	v_lshl_add_u64 v[162:163], s[30:31], 0, v[132:133]
	s_mov_b32 m0, s34
	s_nop 0
	global_load_lds_dwordx4 v[162:163], off
	v_lshl_add_u64 v[162:163], s[30:31], 0, v[136:137]
	s_add_i32 m0, s34, 0x2000
	s_nop 0
	global_load_lds_dwordx4 v[162:163], off
	v_lshl_add_u64 v[162:163], v[220:221], 0, s[10:11]
	s_mov_b32 m0, s43
	s_nop 0
	global_load_lds_dwordx4 v[162:163], off
	v_lshl_add_u64 v[162:163], v[222:223], 0, s[10:11]
	s_mov_b32 m0, s44
	s_nop 0
	global_load_lds_dwordx4 v[162:163], off
	s_waitcnt vmcnt(8)
	s_waitcnt lgkmcnt(0)
	s_barrier
	v_mfma_f32_16x16x32_bf16 v[62:65], v[142:145], v[186:189], v[62:65]
	v_mfma_f32_16x16x32_bf16 v[58:61], v[158:161], v[186:189], v[58:61]
	v_mfma_f32_16x16x32_bf16 v[42:45], v[158:161], v[194:197], v[42:45]
	v_mfma_f32_16x16x32_bf16 v[46:49], v[142:145], v[194:197], v[46:49]
	v_mfma_f32_16x16x32_bf16 v[30:33], v[142:145], v[202:205], v[30:33]
	v_mfma_f32_16x16x32_bf16 v[26:29], v[158:161], v[202:205], v[26:29]
	v_mfma_f32_16x16x32_bf16 v[10:13], v[158:161], v[210:213], v[10:13]
	v_mfma_f32_16x16x32_bf16 v[14:17], v[142:145], v[210:213], v[14:17]
	v_mfma_f32_16x16x32_bf16 v[62:65], v[154:157], v[190:193], v[62:65]
	v_mfma_f32_16x16x32_bf16 v[58:61], v[166:169], v[190:193], v[58:61]
	v_mfma_f32_16x16x32_bf16 v[42:45], v[166:169], v[198:201], v[42:45]
	v_mfma_f32_16x16x32_bf16 v[46:49], v[154:157], v[198:201], v[46:49]
	v_mfma_f32_16x16x32_bf16 v[30:33], v[154:157], v[206:209], v[30:33]
	v_mfma_f32_16x16x32_bf16 v[26:29], v[166:169], v[206:209], v[26:29]
	v_mfma_f32_16x16x32_bf16 v[10:13], v[166:169], v[214:217], v[10:13]
	v_mfma_f32_16x16x32_bf16 v[14:17], v[154:157], v[214:217], v[14:17]
	v_mfma_f32_16x16x32_bf16 v[54:57], v[170:173], v[186:189], v[54:57]
	v_mfma_f32_16x16x32_bf16 v[50:53], v[178:181], v[186:189], v[50:53]
	v_mfma_f32_16x16x32_bf16 v[34:37], v[178:181], v[194:197], v[34:37]
	v_mfma_f32_16x16x32_bf16 v[38:41], v[170:173], v[194:197], v[38:41]
	v_mfma_f32_16x16x32_bf16 v[22:25], v[170:173], v[202:205], v[22:25]
	v_mfma_f32_16x16x32_bf16 v[18:21], v[178:181], v[202:205], v[18:21]
	v_mfma_f32_16x16x32_bf16 v[2:5], v[178:181], v[210:213], v[2:5]
	v_mfma_f32_16x16x32_bf16 v[6:9], v[170:173], v[210:213], v[6:9]
	v_mfma_f32_16x16x32_bf16 v[54:57], v[174:177], v[190:193], v[54:57]
	v_mfma_f32_16x16x32_bf16 v[50:53], v[182:185], v[190:193], v[50:53]
	v_mfma_f32_16x16x32_bf16 v[34:37], v[182:185], v[198:201], v[34:37]
	v_mfma_f32_16x16x32_bf16 v[38:41], v[174:177], v[198:201], v[38:41]
	v_mfma_f32_16x16x32_bf16 v[22:25], v[174:177], v[206:209], v[22:25]
	v_mfma_f32_16x16x32_bf16 v[18:21], v[182:185], v[206:209], v[18:21]
	v_mfma_f32_16x16x32_bf16 v[2:5], v[182:185], v[214:217], v[2:5]
	v_mfma_f32_16x16x32_bf16 v[6:9], v[174:177], v[214:217], v[6:9]
	s_barrier
	s_add_i32 s51, s51, 2
	s_add_u32 s28, s28, 0x100
	s_addc_u32 s29, s29, 0
	s_add_u32 s49, s49, 0x100
	s_addc_u32 s50, s50, 0
	s_cmp_gt_u32 s51, 5
	s_cbranch_scc0 .LBB0_1220
	s_setprio 0
	s_lshl_b32 s98, s26, 8
	s_add_i32 s98, s98, s41
	v_add_u32_e32 v240, s98, v146
	s_lshl_b32 s98, s0, 8
	s_or_b32 s98, s98, s42
	v_lshl_add_u32 v241, v147, 3, s98
	v_lshlrev_b32_e32 v240, 12, v240
	v_lshl_add_u32 v240, v241, 1, v240
	global_load_dwordx4 v[168:171], v240, s[62:63]
	global_load_dwordx4 v[172:175], v240, s[62:63] offset:256
	v_add_u32_e32 v240, 0x10000, v240
	global_load_dwordx4 v[176:179], v240, s[62:63]
	global_load_dwordx4 v[180:183], v240, s[62:63] offset:256
	v_add_u32_e32 v240, 0x10000, v240
	global_load_dwordx4 v[184:187], v240, s[62:63]
	global_load_dwordx4 v[188:191], v240, s[62:63] offset:256
	v_add_u32_e32 v240, 0x10000, v240
	global_load_dwordx4 v[192:195], v240, s[62:63]
	global_load_dwordx4 v[196:199], v240, s[62:63] offset:256
	v_add_u32_e32 v240, 0x50000, v240
	global_load_dwordx4 v[200:203], v240, s[62:63]
	global_load_dwordx4 v[204:207], v240, s[62:63] offset:256
	v_add_u32_e32 v240, 0x10000, v240
	global_load_dwordx4 v[208:211], v240, s[62:63]
	global_load_dwordx4 v[212:215], v240, s[62:63] offset:256
	v_add_u32_e32 v240, 0x10000, v240
	global_load_dwordx4 v[216:219], v240, s[62:63]
	global_load_dwordx4 v[220:223], v240, s[62:63] offset:256
	v_add_u32_e32 v240, 0x10000, v240
	global_load_dwordx4 v[224:227], v240, s[62:63]
	global_load_dwordx4 v[232:235], v240, s[62:63] offset:256
	s_and_b64 vcc, exec, s[12:13]
	s_cbranch_vccz .LBB0_1223
	s_barrier

.Lsp_p10:
.LBB0_1337:
	ds_read_b128 v[142:145], v149
	ds_read_b128 v[154:157], v149 offset:1024
	ds_read_b128 v[158:161], v149 offset:2048
	ds_read_b128 v[166:169], v149 offset:3072
	ds_read_b128 v[170:173], v150
	ds_read_b128 v[174:177], v150 offset:1024
	ds_read_b128 v[178:181], v150 offset:2048
	ds_read_b128 v[182:185], v150 offset:3072
	s_add_u32 s30, s28, 0xfff80080
	s_addc_u32 s31, s29, -1
	s_cmp_eq_u32 s54, 28
	s_cselect_b32 s35, s17, s31
	s_cselect_b32 s34, s19, s30
	s_cselect_b32 s31, s50, s53
	s_cselect_b32 s30, s51, s52
	v_lshl_add_u64 v[162:163], s[28:29], 0, v[138:139]
	s_add_i32 m0, s25, 0xc000
	ds_read_b128 v[186:189], v151
	ds_read_b128 v[190:193], v151 offset:1024
	ds_read_b128 v[194:197], v151 offset:2048
	ds_read_b128 v[198:201], v151 offset:3072
	ds_read_b128 v[202:205], v151 offset:4096
	ds_read_b128 v[206:209], v151 offset:5120
	ds_read_b128 v[210:213], v151 offset:6144
	ds_read_b128 v[214:217], v151 offset:7168
	global_load_lds_dwordx4 v[162:163], off
	v_lshl_add_u64 v[162:163], s[28:29], 0, v[140:141]
	s_add_i32 m0, s25, 0xe000
	s_nop 0
	global_load_lds_dwordx4 v[162:163], off
	s_waitcnt vmcnt(8)
	s_waitcnt lgkmcnt(0)
	s_barrier
	v_mfma_f32_16x16x32_bf16 v[122:125], v[142:145], v[186:189], v[122:125]
	v_mfma_f32_16x16x32_bf16 v[114:117], v[158:161], v[186:189], v[114:117]
	v_mfma_f32_16x16x32_bf16 v[98:101], v[158:161], v[194:197], v[98:101]
	v_mfma_f32_16x16x32_bf16 v[106:109], v[142:145], v[194:197], v[106:109]
	v_mfma_f32_16x16x32_bf16 v[90:93], v[142:145], v[202:205], v[90:93]
	v_mfma_f32_16x16x32_bf16 v[82:85], v[158:161], v[202:205], v[82:85]
	v_mfma_f32_16x16x32_bf16 v[66:69], v[158:161], v[210:213], v[66:69]
	v_mfma_f32_16x16x32_bf16 v[74:77], v[142:145], v[210:213], v[74:77]
	v_mfma_f32_16x16x32_bf16 v[122:125], v[154:157], v[190:193], v[122:125]
	v_mfma_f32_16x16x32_bf16 v[114:117], v[166:169], v[190:193], v[114:117]
	v_mfma_f32_16x16x32_bf16 v[98:101], v[166:169], v[198:201], v[98:101]
	v_mfma_f32_16x16x32_bf16 v[106:109], v[154:157], v[198:201], v[106:109]
	v_mfma_f32_16x16x32_bf16 v[90:93], v[154:157], v[206:209], v[90:93]
	v_mfma_f32_16x16x32_bf16 v[82:85], v[166:169], v[206:209], v[82:85]
	v_mfma_f32_16x16x32_bf16 v[66:69], v[166:169], v[214:217], v[66:69]
	v_mfma_f32_16x16x32_bf16 v[74:77], v[154:157], v[214:217], v[74:77]
	v_mfma_f32_16x16x32_bf16 v[126:129], v[170:173], v[186:189], v[126:129]
	v_mfma_f32_16x16x32_bf16 v[118:121], v[178:181], v[186:189], v[118:121]
	v_mfma_f32_16x16x32_bf16 v[102:105], v[178:181], v[194:197], v[102:105]
	v_mfma_f32_16x16x32_bf16 v[110:113], v[170:173], v[194:197], v[110:113]
	v_mfma_f32_16x16x32_bf16 v[94:97], v[170:173], v[202:205], v[94:97]
	v_mfma_f32_16x16x32_bf16 v[86:89], v[178:181], v[202:205], v[86:89]
	v_mfma_f32_16x16x32_bf16 v[70:73], v[178:181], v[210:213], v[70:73]
	v_mfma_f32_16x16x32_bf16 v[78:81], v[170:173], v[210:213], v[78:81]
	v_mfma_f32_16x16x32_bf16 v[126:129], v[174:177], v[190:193], v[126:129]
	v_mfma_f32_16x16x32_bf16 v[118:121], v[182:185], v[190:193], v[118:121]
	v_mfma_f32_16x16x32_bf16 v[102:105], v[182:185], v[198:201], v[102:105]
	v_mfma_f32_16x16x32_bf16 v[110:113], v[174:177], v[198:201], v[110:113]
	v_mfma_f32_16x16x32_bf16 v[94:97], v[174:177], v[206:209], v[94:97]
	v_mfma_f32_16x16x32_bf16 v[86:89], v[182:185], v[206:209], v[86:89]
	v_mfma_f32_16x16x32_bf16 v[70:73], v[182:185], v[214:217], v[70:73]
	v_mfma_f32_16x16x32_bf16 v[78:81], v[174:177], v[214:217], v[78:81]
	s_barrier
	s_add_i32 s55, s46, s36
	v_lshl_add_u64 v[162:163], s[30:31], 0, v[132:133]
	s_mov_b32 m0, s55
	ds_read_b128 v[186:189], v151 offset:16384
	ds_read_b128 v[190:193], v151 offset:17408
	ds_read_b128 v[194:197], v151 offset:18432
	ds_read_b128 v[198:201], v151 offset:19456
	ds_read_b128 v[202:205], v151 offset:20480
	ds_read_b128 v[206:209], v151 offset:21504
	ds_read_b128 v[210:213], v151 offset:22528
	ds_read_b128 v[214:217], v151 offset:23552
	global_load_lds_dwordx4 v[162:163], off
	s_add_i32 m0, s55, 0x2000
	s_add_u32 s56, s30, 0x80000
	v_lshl_add_u64 v[218:219], s[30:31], 0, v[136:137]
	s_addc_u32 s57, s31, 0
	s_add_i32 s55, s47, s36
	global_load_lds_dwordx4 v[218:219], off
	v_lshl_add_u64 v[220:221], s[56:57], 0, v[132:133]
	s_mov_b32 m0, s55
	v_lshl_add_u64 v[222:223], s[34:35], 0, v[134:135]
	global_load_lds_dwordx4 v[220:221], off
	v_lshl_add_u64 v[220:221], s[56:57], 0, v[136:137]
	s_add_i32 m0, s55, 0x2000
	s_nop 0
	global_load_lds_dwordx4 v[220:221], off
	v_lshl_add_u64 v[220:221], s[34:35], 0, v[130:131]
	s_mov_b32 m0, s25
	s_nop 0
	global_load_lds_dwordx4 v[220:221], off
	s_mov_b32 m0, s27
	s_nop 0
	global_load_lds_dwordx4 v[222:223], off
	s_waitcnt vmcnt(8)
	s_waitcnt lgkmcnt(0)
	s_barrier
	v_mfma_f32_16x16x32_bf16 v[58:61], v[142:145], v[186:189], v[58:61]
	v_mfma_f32_16x16x32_bf16 v[50:53], v[158:161], v[186:189], v[50:53]
	v_mfma_f32_16x16x32_bf16 v[34:37], v[158:161], v[194:197], v[34:37]
	v_mfma_f32_16x16x32_bf16 v[42:45], v[142:145], v[194:197], v[42:45]
	v_mfma_f32_16x16x32_bf16 v[26:29], v[142:145], v[202:205], v[26:29]
	v_mfma_f32_16x16x32_bf16 v[18:21], v[158:161], v[202:205], v[18:21]
	v_mfma_f32_16x16x32_bf16 v[2:5], v[158:161], v[210:213], v[2:5]
	v_mfma_f32_16x16x32_bf16 v[10:13], v[142:145], v[210:213], v[10:13]
	v_mfma_f32_16x16x32_bf16 v[58:61], v[154:157], v[190:193], v[58:61]
	v_mfma_f32_16x16x32_bf16 v[50:53], v[166:169], v[190:193], v[50:53]
	v_mfma_f32_16x16x32_bf16 v[34:37], v[166:169], v[198:201], v[34:37]
	v_mfma_f32_16x16x32_bf16 v[42:45], v[154:157], v[198:201], v[42:45]
	v_mfma_f32_16x16x32_bf16 v[26:29], v[154:157], v[206:209], v[26:29]
	v_mfma_f32_16x16x32_bf16 v[18:21], v[166:169], v[206:209], v[18:21]
	v_mfma_f32_16x16x32_bf16 v[2:5], v[166:169], v[214:217], v[2:5]
	v_mfma_f32_16x16x32_bf16 v[10:13], v[154:157], v[214:217], v[10:13]
	v_mfma_f32_16x16x32_bf16 v[62:65], v[170:173], v[186:189], v[62:65]
	v_mfma_f32_16x16x32_bf16 v[54:57], v[178:181], v[186:189], v[54:57]
	v_mfma_f32_16x16x32_bf16 v[38:41], v[178:181], v[194:197], v[38:41]
	v_mfma_f32_16x16x32_bf16 v[46:49], v[170:173], v[194:197], v[46:49]
	v_mfma_f32_16x16x32_bf16 v[30:33], v[170:173], v[202:205], v[30:33]
	v_mfma_f32_16x16x32_bf16 v[22:25], v[178:181], v[202:205], v[22:25]
	v_mfma_f32_16x16x32_bf16 v[6:9], v[178:181], v[210:213], v[6:9]
	v_mfma_f32_16x16x32_bf16 v[14:17], v[170:173], v[210:213], v[14:17]
	v_mfma_f32_16x16x32_bf16 v[62:65], v[174:177], v[190:193], v[62:65]
	v_mfma_f32_16x16x32_bf16 v[54:57], v[182:185], v[190:193], v[54:57]
	v_mfma_f32_16x16x32_bf16 v[38:41], v[182:185], v[198:201], v[38:41]
	v_mfma_f32_16x16x32_bf16 v[46:49], v[174:177], v[198:201], v[46:49]
	v_mfma_f32_16x16x32_bf16 v[30:33], v[174:177], v[206:209], v[30:33]
	v_mfma_f32_16x16x32_bf16 v[22:25], v[182:185], v[206:209], v[22:25]
	v_mfma_f32_16x16x32_bf16 v[6:9], v[182:185], v[214:217], v[6:9]
	v_mfma_f32_16x16x32_bf16 v[14:17], v[174:177], v[214:217], v[14:17]
	s_barrier
	s_add_i32 s55, 0, 0x18000
	v_add_u32_e32 v153, s55, v148
	s_add_i32 s56, 0, 0x1c000
	ds_read_b128 v[142:145], v153
	ds_read_b128 v[154:157], v153 offset:1024
	ds_read_b128 v[158:161], v153 offset:2048
	ds_read_b128 v[166:169], v153 offset:3072
	v_add_u32_e32 v153, s56, v148
	ds_read_b128 v[170:173], v153
	ds_read_b128 v[174:177], v153 offset:1024
	ds_read_b128 v[178:181], v153 offset:2048
	ds_read_b128 v[182:185], v153 offset:3072
	s_add_u32 s34, s34, 0x80000
	s_addc_u32 s35, s35, 0
	s_mov_b32 m0, s37
	v_lshl_add_u64 v[224:225], s[34:35], 0, v[130:131]
	ds_read_b128 v[186:189], v151 offset:32768
	ds_read_b128 v[190:193], v151 offset:33792
	ds_read_b128 v[194:197], v151 offset:34816
	ds_read_b128 v[198:201], v151 offset:35840
	ds_read_b128 v[202:205], v151 offset:36864
	ds_read_b128 v[206:209], v151 offset:37888
	ds_read_b128 v[210:213], v151 offset:38912
	ds_read_b128 v[214:217], v151 offset:39936
	global_load_lds_dwordx4 v[224:225], off
	v_lshl_add_u64 v[224:225], s[34:35], 0, v[134:135]
	s_mov_b32 m0, s38
	s_nop 0
	global_load_lds_dwordx4 v[224:225], off
	s_waitcnt vmcnt(8)
	s_waitcnt lgkmcnt(0)
	s_barrier
	v_mfma_f32_16x16x32_bf16 v[122:125], v[142:145], v[186:189], v[122:125]
	v_mfma_f32_16x16x32_bf16 v[114:117], v[158:161], v[186:189], v[114:117]
	v_mfma_f32_16x16x32_bf16 v[98:101], v[158:161], v[194:197], v[98:101]
	v_mfma_f32_16x16x32_bf16 v[106:109], v[142:145], v[194:197], v[106:109]
	v_mfma_f32_16x16x32_bf16 v[90:93], v[142:145], v[202:205], v[90:93]
	v_mfma_f32_16x16x32_bf16 v[82:85], v[158:161], v[202:205], v[82:85]
	v_mfma_f32_16x16x32_bf16 v[66:69], v[158:161], v[210:213], v[66:69]
	v_mfma_f32_16x16x32_bf16 v[74:77], v[142:145], v[210:213], v[74:77]
	v_mfma_f32_16x16x32_bf16 v[122:125], v[154:157], v[190:193], v[122:125]
	v_mfma_f32_16x16x32_bf16 v[114:117], v[166:169], v[190:193], v[114:117]
	v_mfma_f32_16x16x32_bf16 v[98:101], v[166:169], v[198:201], v[98:101]
	v_mfma_f32_16x16x32_bf16 v[106:109], v[154:157], v[198:201], v[106:109]
	v_mfma_f32_16x16x32_bf16 v[90:93], v[154:157], v[206:209], v[90:93]
	v_mfma_f32_16x16x32_bf16 v[82:85], v[166:169], v[206:209], v[82:85]
	v_mfma_f32_16x16x32_bf16 v[66:69], v[166:169], v[214:217], v[66:69]
	v_mfma_f32_16x16x32_bf16 v[74:77], v[154:157], v[214:217], v[74:77]
	v_mfma_f32_16x16x32_bf16 v[126:129], v[170:173], v[186:189], v[126:129]
	v_mfma_f32_16x16x32_bf16 v[118:121], v[178:181], v[186:189], v[118:121]
	v_mfma_f32_16x16x32_bf16 v[102:105], v[178:181], v[194:197], v[102:105]
	v_mfma_f32_16x16x32_bf16 v[110:113], v[170:173], v[194:197], v[110:113]
	v_mfma_f32_16x16x32_bf16 v[94:97], v[170:173], v[202:205], v[94:97]
	v_mfma_f32_16x16x32_bf16 v[86:89], v[178:181], v[202:205], v[86:89]
	v_mfma_f32_16x16x32_bf16 v[70:73], v[178:181], v[210:213], v[70:73]
	v_mfma_f32_16x16x32_bf16 v[78:81], v[170:173], v[210:213], v[78:81]
	v_mfma_f32_16x16x32_bf16 v[126:129], v[174:177], v[190:193], v[126:129]
	v_mfma_f32_16x16x32_bf16 v[118:121], v[182:185], v[190:193], v[118:121]
	v_mfma_f32_16x16x32_bf16 v[102:105], v[182:185], v[198:201], v[102:105]
	v_mfma_f32_16x16x32_bf16 v[110:113], v[174:177], v[198:201], v[110:113]
	v_mfma_f32_16x16x32_bf16 v[94:97], v[174:177], v[206:209], v[94:97]
	v_mfma_f32_16x16x32_bf16 v[86:89], v[182:185], v[206:209], v[86:89]
	v_mfma_f32_16x16x32_bf16 v[70:73], v[182:185], v[214:217], v[70:73]
	v_mfma_f32_16x16x32_bf16 v[78:81], v[174:177], v[214:217], v[78:81]
	s_barrier
	s_add_i32 s34, s55, s36
	v_lshl_add_u64 v[162:163], v[162:163], 0, s[12:13]
	s_mov_b32 m0, s34
	ds_read_b128 v[186:189], v151 offset:49152
	ds_read_b128 v[190:193], v151 offset:50176
	ds_read_b128 v[194:197], v151 offset:51200
	ds_read_b128 v[198:201], v151 offset:52224
	ds_read_b128 v[202:205], v151 offset:53248
	ds_read_b128 v[206:209], v151 offset:54272
	ds_read_b128 v[210:213], v151 offset:55296
	ds_read_b128 v[214:217], v151 offset:56320
	global_load_lds_dwordx4 v[162:163], off
	s_add_i32 m0, s34, 0x2000
	s_add_u32 s30, s30, 0x80080
	v_lshl_add_u64 v[162:163], v[218:219], 0, s[12:13]
	s_addc_u32 s31, s31, 0
	s_add_i32 s34, s56, s36
	global_load_lds_dwordx4 v[162:163], off
	v_lshl_add_u64 v[162:163], s[30:31], 0, v[132:133]
	s_mov_b32 m0, s34
	s_nop 0
	global_load_lds_dwordx4 v[162:163], off
	v_lshl_add_u64 v[162:163], s[30:31], 0, v[136:137]
	s_add_i32 m0, s34, 0x2000
	s_nop 0
	global_load_lds_dwordx4 v[162:163], off
	v_lshl_add_u64 v[162:163], v[220:221], 0, s[12:13]
	s_mov_b32 m0, s42
	s_nop 0
	global_load_lds_dwordx4 v[162:163], off
	v_lshl_add_u64 v[162:163], v[222:223], 0, s[12:13]
	s_mov_b32 m0, s43
	s_nop 0
	global_load_lds_dwordx4 v[162:163], off
	s_waitcnt vmcnt(8)
	s_waitcnt lgkmcnt(0)
	s_barrier
	v_mfma_f32_16x16x32_bf16 v[58:61], v[142:145], v[186:189], v[58:61]
	v_mfma_f32_16x16x32_bf16 v[50:53], v[158:161], v[186:189], v[50:53]
	v_mfma_f32_16x16x32_bf16 v[34:37], v[158:161], v[194:197], v[34:37]
	v_mfma_f32_16x16x32_bf16 v[42:45], v[142:145], v[194:197], v[42:45]
	v_mfma_f32_16x16x32_bf16 v[26:29], v[142:145], v[202:205], v[26:29]
	v_mfma_f32_16x16x32_bf16 v[18:21], v[158:161], v[202:205], v[18:21]
	v_mfma_f32_16x16x32_bf16 v[2:5], v[158:161], v[210:213], v[2:5]
	v_mfma_f32_16x16x32_bf16 v[10:13], v[142:145], v[210:213], v[10:13]
	v_mfma_f32_16x16x32_bf16 v[58:61], v[154:157], v[190:193], v[58:61]
	v_mfma_f32_16x16x32_bf16 v[50:53], v[166:169], v[190:193], v[50:53]
	v_mfma_f32_16x16x32_bf16 v[34:37], v[166:169], v[198:201], v[34:37]
	v_mfma_f32_16x16x32_bf16 v[42:45], v[154:157], v[198:201], v[42:45]
	v_mfma_f32_16x16x32_bf16 v[26:29], v[154:157], v[206:209], v[26:29]
	v_mfma_f32_16x16x32_bf16 v[18:21], v[166:169], v[206:209], v[18:21]
	v_mfma_f32_16x16x32_bf16 v[2:5], v[166:169], v[214:217], v[2:5]
	v_mfma_f32_16x16x32_bf16 v[10:13], v[154:157], v[214:217], v[10:13]
	v_mfma_f32_16x16x32_bf16 v[62:65], v[170:173], v[186:189], v[62:65]
	v_mfma_f32_16x16x32_bf16 v[54:57], v[178:181], v[186:189], v[54:57]
	v_mfma_f32_16x16x32_bf16 v[38:41], v[178:181], v[194:197], v[38:41]
	v_mfma_f32_16x16x32_bf16 v[46:49], v[170:173], v[194:197], v[46:49]
	v_mfma_f32_16x16x32_bf16 v[30:33], v[170:173], v[202:205], v[30:33]
	v_mfma_f32_16x16x32_bf16 v[22:25], v[178:181], v[202:205], v[22:25]
	v_mfma_f32_16x16x32_bf16 v[6:9], v[178:181], v[210:213], v[6:9]
	v_mfma_f32_16x16x32_bf16 v[14:17], v[170:173], v[210:213], v[14:17]
	v_mfma_f32_16x16x32_bf16 v[62:65], v[174:177], v[190:193], v[62:65]
	v_mfma_f32_16x16x32_bf16 v[54:57], v[182:185], v[190:193], v[54:57]
	v_mfma_f32_16x16x32_bf16 v[38:41], v[182:185], v[198:201], v[38:41]
	v_mfma_f32_16x16x32_bf16 v[46:49], v[174:177], v[198:201], v[46:49]
	v_mfma_f32_16x16x32_bf16 v[30:33], v[174:177], v[206:209], v[30:33]
	v_mfma_f32_16x16x32_bf16 v[22:25], v[182:185], v[206:209], v[22:25]
	v_mfma_f32_16x16x32_bf16 v[6:9], v[182:185], v[214:217], v[6:9]
	v_mfma_f32_16x16x32_bf16 v[14:17], v[174:177], v[214:217], v[14:17]
	s_barrier
	s_add_i32 s54, s54, 2
	s_add_u32 s28, s28, 0x100
	s_addc_u32 s29, s29, 0
	s_add_u32 s52, s52, 0x100
	s_addc_u32 s53, s53, 0
	s_cmp_gt_u32 s54, 29
	s_cbranch_scc0 .LBB0_1337
	s_setprio 0
	v_mov_b32_e32 v142, v1
	v_mov_b32_e32 v153, v147
	v_mov_b32_e32 v143, v165
	v_mov_b32_e32 v144, v146
	s_lshl_b32 s17, s26, 8
	s_add_i32 s17, s17, s40
	v_add_u32_e32 v142, s17, v144
	v_ashrrev_i32_e32 v143, 31, v142
	v_lshl_add_u64 v[144:145], v[142:143], 2, s[10:11]
	global_load_dword v229, v[144:145], off
	global_load_dword v230, v[144:145], off offset:64
	global_load_dword v231, v[144:145], off offset:128
	global_load_dword v232, v[144:145], off offset:192
	global_load_dword v233, v[144:145], off offset:512
	global_load_dword v234, v[144:145], off offset:576
	global_load_dword v235, v[144:145], off offset:640
	global_load_dword v236, v[144:145], off offset:704
	s_and_b64 vcc, exec, s[14:15]
	s_cbranch_vccz .LBB0_1340
	s_barrier

.Lsp_p11:
.LBB0_1449:
	ds_read_b128 v[140:143], v167
	ds_read_b128 v[144:147], v167 offset:1024
	ds_read_b128 v[148:151], v167 offset:2048
	ds_read_b128 v[152:155], v167 offset:3072
	ds_read_b128 v[156:159], v168
	ds_read_b128 v[172:175], v168 offset:1024
	ds_read_b128 v[176:179], v168 offset:2048
	ds_read_b128 v[180:183], v168 offset:3072
	s_add_u32 s20, s0, 0xffea0080
	s_addc_u32 s21, s1, -1
	s_cmpk_eq_i32 s52, 0x54
	s_cselect_b32 s23, s25, s21
	s_cselect_b32 s22, s47, s20
	s_cselect_b32 s21, s48, s51
	s_cselect_b32 s20, s49, s50
	v_lshl_add_u64 v[160:161], s[0:1], 0, v[136:137]
	s_add_i32 m0, s29, 0xc000
	ds_read_b128 v[184:187], v169
	ds_read_b128 v[188:191], v169 offset:1024
	ds_read_b128 v[192:195], v169 offset:2048
	ds_read_b128 v[196:199], v169 offset:3072
	ds_read_b128 v[200:203], v169 offset:4096
	ds_read_b128 v[204:207], v169 offset:5120
	ds_read_b128 v[208:211], v169 offset:6144
	ds_read_b128 v[212:215], v169 offset:7168
	global_load_lds_dwordx4 v[160:161], off
	v_lshl_add_u64 v[160:161], s[0:1], 0, v[138:139]
	s_add_i32 m0, s29, 0xe000
	s_nop 0
	global_load_lds_dwordx4 v[160:161], off
	s_waitcnt vmcnt(8)
	s_waitcnt lgkmcnt(0)
	s_barrier
	v_mfma_f32_16x16x32_bf16 v[124:127], v[140:143], v[184:187], v[124:127]
	v_mfma_f32_16x16x32_bf16 v[120:123], v[148:151], v[184:187], v[120:123]
	v_mfma_f32_16x16x32_bf16 v[104:107], v[148:151], v[192:195], v[104:107]
	v_mfma_f32_16x16x32_bf16 v[108:111], v[140:143], v[192:195], v[108:111]
	v_mfma_f32_16x16x32_bf16 v[92:95], v[140:143], v[200:203], v[92:95]
	v_mfma_f32_16x16x32_bf16 v[88:91], v[148:151], v[200:203], v[88:91]
	v_mfma_f32_16x16x32_bf16 v[72:75], v[148:151], v[208:211], v[72:75]
	v_mfma_f32_16x16x32_bf16 v[76:79], v[140:143], v[208:211], v[76:79]
	v_mfma_f32_16x16x32_bf16 v[124:127], v[144:147], v[188:191], v[124:127]
	v_mfma_f32_16x16x32_bf16 v[120:123], v[152:155], v[188:191], v[120:123]
	v_mfma_f32_16x16x32_bf16 v[104:107], v[152:155], v[196:199], v[104:107]
	v_mfma_f32_16x16x32_bf16 v[108:111], v[144:147], v[196:199], v[108:111]
	v_mfma_f32_16x16x32_bf16 v[92:95], v[144:147], v[204:207], v[92:95]
	v_mfma_f32_16x16x32_bf16 v[88:91], v[152:155], v[204:207], v[88:91]
	v_mfma_f32_16x16x32_bf16 v[72:75], v[152:155], v[212:215], v[72:75]
	v_mfma_f32_16x16x32_bf16 v[76:79], v[144:147], v[212:215], v[76:79]
	v_mfma_f32_16x16x32_bf16 v[116:119], v[156:159], v[184:187], v[116:119]
	v_mfma_f32_16x16x32_bf16 v[112:115], v[176:179], v[184:187], v[112:115]
	v_mfma_f32_16x16x32_bf16 v[96:99], v[176:179], v[192:195], v[96:99]
	v_mfma_f32_16x16x32_bf16 v[100:103], v[156:159], v[192:195], v[100:103]
	v_mfma_f32_16x16x32_bf16 v[84:87], v[156:159], v[200:203], v[84:87]
	v_mfma_f32_16x16x32_bf16 v[80:83], v[176:179], v[200:203], v[80:83]
	v_mfma_f32_16x16x32_bf16 v[64:67], v[176:179], v[208:211], v[64:67]
	v_mfma_f32_16x16x32_bf16 v[68:71], v[156:159], v[208:211], v[68:71]
	v_mfma_f32_16x16x32_bf16 v[116:119], v[172:175], v[188:191], v[116:119]
	v_mfma_f32_16x16x32_bf16 v[112:115], v[180:183], v[188:191], v[112:115]
	v_mfma_f32_16x16x32_bf16 v[96:99], v[180:183], v[196:199], v[96:99]
	v_mfma_f32_16x16x32_bf16 v[100:103], v[172:175], v[196:199], v[100:103]
	v_mfma_f32_16x16x32_bf16 v[84:87], v[172:175], v[204:207], v[84:87]
	v_mfma_f32_16x16x32_bf16 v[80:83], v[180:183], v[204:207], v[80:83]
	v_mfma_f32_16x16x32_bf16 v[64:67], v[180:183], v[212:215], v[64:67]
	v_mfma_f32_16x16x32_bf16 v[68:71], v[172:175], v[212:215], v[68:71]
	s_barrier
	s_add_i32 s53, s42, s28
	v_lshl_add_u64 v[160:161], s[20:21], 0, v[130:131]
	s_mov_b32 m0, s53
	ds_read_b128 v[184:187], v169 offset:16384
	ds_read_b128 v[188:191], v169 offset:17408
	ds_read_b128 v[192:195], v169 offset:18432
	ds_read_b128 v[196:199], v169 offset:19456
	ds_read_b128 v[200:203], v169 offset:20480
	ds_read_b128 v[204:207], v169 offset:21504
	ds_read_b128 v[208:211], v169 offset:22528
	ds_read_b128 v[212:215], v169 offset:23552
	global_load_lds_dwordx4 v[160:161], off
	s_add_i32 m0, s53, 0x2000
	s_add_u32 s54, s20, 0x160000
	v_lshl_add_u64 v[216:217], s[20:21], 0, v[134:135]
	s_addc_u32 s55, s21, 0
	s_add_i32 s53, s43, s28
	global_load_lds_dwordx4 v[216:217], off
	v_lshl_add_u64 v[218:219], s[54:55], 0, v[130:131]
	s_mov_b32 m0, s53
	v_lshl_add_u64 v[220:221], s[22:23], 0, v[132:133]
	global_load_lds_dwordx4 v[218:219], off
	v_lshl_add_u64 v[218:219], s[54:55], 0, v[134:135]
	s_add_i32 m0, s53, 0x2000
	s_nop 0
	global_load_lds_dwordx4 v[218:219], off
	v_lshl_add_u64 v[218:219], s[22:23], 0, v[128:129]
	s_mov_b32 m0, s29
	s_nop 0
	global_load_lds_dwordx4 v[218:219], off
	s_mov_b32 m0, s30
	s_nop 0
	global_load_lds_dwordx4 v[220:221], off
	s_waitcnt vmcnt(8)
	s_waitcnt lgkmcnt(0)
	s_barrier
	v_mfma_f32_16x16x32_bf16 v[60:63], v[140:143], v[184:187], v[60:63]
	v_mfma_f32_16x16x32_bf16 v[56:59], v[148:151], v[184:187], v[56:59]
	v_mfma_f32_16x16x32_bf16 v[40:43], v[148:151], v[192:195], v[40:43]
	v_mfma_f32_16x16x32_bf16 v[44:47], v[140:143], v[192:195], v[44:47]
	v_mfma_f32_16x16x32_bf16 v[28:31], v[140:143], v[200:203], v[28:31]
	v_mfma_f32_16x16x32_bf16 v[24:27], v[148:151], v[200:203], v[24:27]
	v_mfma_f32_16x16x32_bf16 v[8:11], v[148:151], v[208:211], v[8:11]
	v_mfma_f32_16x16x32_bf16 v[12:15], v[140:143], v[208:211], v[12:15]
	v_mfma_f32_16x16x32_bf16 v[60:63], v[144:147], v[188:191], v[60:63]
	v_mfma_f32_16x16x32_bf16 v[56:59], v[152:155], v[188:191], v[56:59]
	v_mfma_f32_16x16x32_bf16 v[40:43], v[152:155], v[196:199], v[40:43]
	v_mfma_f32_16x16x32_bf16 v[44:47], v[144:147], v[196:199], v[44:47]
	v_mfma_f32_16x16x32_bf16 v[28:31], v[144:147], v[204:207], v[28:31]
	v_mfma_f32_16x16x32_bf16 v[24:27], v[152:155], v[204:207], v[24:27]
	v_mfma_f32_16x16x32_bf16 v[8:11], v[152:155], v[212:215], v[8:11]
	v_mfma_f32_16x16x32_bf16 v[12:15], v[144:147], v[212:215], v[12:15]
	v_mfma_f32_16x16x32_bf16 v[52:55], v[156:159], v[184:187], v[52:55]
	v_mfma_f32_16x16x32_bf16 v[48:51], v[176:179], v[184:187], v[48:51]
	v_mfma_f32_16x16x32_bf16 v[32:35], v[176:179], v[192:195], v[32:35]
	v_mfma_f32_16x16x32_bf16 v[36:39], v[156:159], v[192:195], v[36:39]
	v_mfma_f32_16x16x32_bf16 v[20:23], v[156:159], v[200:203], v[20:23]
	v_mfma_f32_16x16x32_bf16 v[16:19], v[176:179], v[200:203], v[16:19]
	v_mfma_f32_16x16x32_bf16 v[0:3], v[176:179], v[208:211], v[0:3]
	v_mfma_f32_16x16x32_bf16 v[4:7], v[156:159], v[208:211], v[4:7]
	v_mfma_f32_16x16x32_bf16 v[52:55], v[172:175], v[188:191], v[52:55]
	v_mfma_f32_16x16x32_bf16 v[48:51], v[180:183], v[188:191], v[48:51]
	v_mfma_f32_16x16x32_bf16 v[32:35], v[180:183], v[196:199], v[32:35]
	v_mfma_f32_16x16x32_bf16 v[36:39], v[172:175], v[196:199], v[36:39]
	v_mfma_f32_16x16x32_bf16 v[20:23], v[172:175], v[204:207], v[20:23]
	v_mfma_f32_16x16x32_bf16 v[16:19], v[180:183], v[204:207], v[16:19]
	v_mfma_f32_16x16x32_bf16 v[0:3], v[180:183], v[212:215], v[0:3]
	v_mfma_f32_16x16x32_bf16 v[4:7], v[172:175], v[212:215], v[4:7]
	s_barrier
	s_add_i32 s53, 0, 0x18000
	s_add_i32 s54, 0, 0x1c000
	v_add_u32_e32 v152, s53, v166
	v_add_u32_e32 v180, s54, v166
	ds_read_b128 v[140:143], v152
	ds_read_b128 v[144:147], v152 offset:1024
	ds_read_b128 v[148:151], v152 offset:2048
	ds_read_b128 v[152:155], v152 offset:3072
	ds_read_b128 v[156:159], v180
	ds_read_b128 v[172:175], v180 offset:1024
	ds_read_b128 v[176:179], v180 offset:2048
	ds_read_b128 v[180:183], v180 offset:3072
	s_add_u32 s22, s22, 0x160000
	s_addc_u32 s23, s23, 0
	s_mov_b32 m0, s31
	v_lshl_add_u64 v[222:223], s[22:23], 0, v[128:129]
	ds_read_b128 v[184:187], v169 offset:32768
	ds_read_b128 v[188:191], v169 offset:33792
	ds_read_b128 v[192:195], v169 offset:34816
	ds_read_b128 v[196:199], v169 offset:35840
	ds_read_b128 v[200:203], v169 offset:36864
	ds_read_b128 v[204:207], v169 offset:37888
	ds_read_b128 v[208:211], v169 offset:38912
	ds_read_b128 v[212:215], v169 offset:39936
	global_load_lds_dwordx4 v[222:223], off
	v_lshl_add_u64 v[222:223], s[22:23], 0, v[132:133]
	s_mov_b32 m0, s33
	s_nop 0
	global_load_lds_dwordx4 v[222:223], off
	s_waitcnt vmcnt(8)
	s_waitcnt lgkmcnt(0)
	s_barrier
	v_mfma_f32_16x16x32_bf16 v[124:127], v[140:143], v[184:187], v[124:127]
	v_mfma_f32_16x16x32_bf16 v[120:123], v[148:151], v[184:187], v[120:123]
	v_mfma_f32_16x16x32_bf16 v[104:107], v[148:151], v[192:195], v[104:107]
	v_mfma_f32_16x16x32_bf16 v[108:111], v[140:143], v[192:195], v[108:111]
	v_mfma_f32_16x16x32_bf16 v[92:95], v[140:143], v[200:203], v[92:95]
	v_mfma_f32_16x16x32_bf16 v[88:91], v[148:151], v[200:203], v[88:91]
	v_mfma_f32_16x16x32_bf16 v[72:75], v[148:151], v[208:211], v[72:75]
	v_mfma_f32_16x16x32_bf16 v[76:79], v[140:143], v[208:211], v[76:79]
	v_mfma_f32_16x16x32_bf16 v[124:127], v[144:147], v[188:191], v[124:127]
	v_mfma_f32_16x16x32_bf16 v[120:123], v[152:155], v[188:191], v[120:123]
	v_mfma_f32_16x16x32_bf16 v[104:107], v[152:155], v[196:199], v[104:107]
	v_mfma_f32_16x16x32_bf16 v[108:111], v[144:147], v[196:199], v[108:111]
	v_mfma_f32_16x16x32_bf16 v[92:95], v[144:147], v[204:207], v[92:95]
	v_mfma_f32_16x16x32_bf16 v[88:91], v[152:155], v[204:207], v[88:91]
	v_mfma_f32_16x16x32_bf16 v[72:75], v[152:155], v[212:215], v[72:75]
	v_mfma_f32_16x16x32_bf16 v[76:79], v[144:147], v[212:215], v[76:79]
	v_mfma_f32_16x16x32_bf16 v[116:119], v[156:159], v[184:187], v[116:119]
	v_mfma_f32_16x16x32_bf16 v[112:115], v[176:179], v[184:187], v[112:115]
	v_mfma_f32_16x16x32_bf16 v[96:99], v[176:179], v[192:195], v[96:99]
	v_mfma_f32_16x16x32_bf16 v[100:103], v[156:159], v[192:195], v[100:103]
	v_mfma_f32_16x16x32_bf16 v[84:87], v[156:159], v[200:203], v[84:87]
	v_mfma_f32_16x16x32_bf16 v[80:83], v[176:179], v[200:203], v[80:83]
	v_mfma_f32_16x16x32_bf16 v[64:67], v[176:179], v[208:211], v[64:67]
	v_mfma_f32_16x16x32_bf16 v[68:71], v[156:159], v[208:211], v[68:71]
	v_mfma_f32_16x16x32_bf16 v[116:119], v[172:175], v[188:191], v[116:119]
	v_mfma_f32_16x16x32_bf16 v[112:115], v[180:183], v[188:191], v[112:115]
	v_mfma_f32_16x16x32_bf16 v[96:99], v[180:183], v[196:199], v[96:99]
	v_mfma_f32_16x16x32_bf16 v[100:103], v[172:175], v[196:199], v[100:103]
	v_mfma_f32_16x16x32_bf16 v[84:87], v[172:175], v[204:207], v[84:87]
	v_mfma_f32_16x16x32_bf16 v[80:83], v[180:183], v[204:207], v[80:83]
	v_mfma_f32_16x16x32_bf16 v[64:67], v[180:183], v[212:215], v[64:67]
	v_mfma_f32_16x16x32_bf16 v[68:71], v[172:175], v[212:215], v[68:71]
	s_barrier
	s_add_i32 s22, s53, s28
	v_lshl_add_u64 v[160:161], v[160:161], 0, s[8:9]
	s_mov_b32 m0, s22
	ds_read_b128 v[184:187], v169 offset:49152
	ds_read_b128 v[188:191], v169 offset:50176
	ds_read_b128 v[192:195], v169 offset:51200
	ds_read_b128 v[196:199], v169 offset:52224
	ds_read_b128 v[200:203], v169 offset:53248
	ds_read_b128 v[204:207], v169 offset:54272
	ds_read_b128 v[208:211], v169 offset:55296
	ds_read_b128 v[212:215], v169 offset:56320
	global_load_lds_dwordx4 v[160:161], off
	s_add_i32 m0, s22, 0x2000
	s_add_u32 s20, s20, 0x160080
	v_lshl_add_u64 v[160:161], v[216:217], 0, s[8:9]
	s_addc_u32 s21, s21, 0
	s_add_i32 s22, s54, s28
	global_load_lds_dwordx4 v[160:161], off
	v_lshl_add_u64 v[160:161], s[20:21], 0, v[130:131]
	s_mov_b32 m0, s22
	s_nop 0
	global_load_lds_dwordx4 v[160:161], off
	v_lshl_add_u64 v[160:161], s[20:21], 0, v[134:135]
	s_add_i32 m0, s22, 0x2000
	s_nop 0
	global_load_lds_dwordx4 v[160:161], off
	v_lshl_add_u64 v[160:161], v[218:219], 0, s[8:9]
	s_mov_b32 m0, s39
	s_nop 0
	global_load_lds_dwordx4 v[160:161], off
	v_lshl_add_u64 v[160:161], v[220:221], 0, s[8:9]
	s_mov_b32 m0, s40
	s_nop 0
	global_load_lds_dwordx4 v[160:161], off
	s_waitcnt vmcnt(8)
	s_waitcnt lgkmcnt(0)
	s_barrier
	v_mfma_f32_16x16x32_bf16 v[60:63], v[140:143], v[184:187], v[60:63]
	v_mfma_f32_16x16x32_bf16 v[56:59], v[148:151], v[184:187], v[56:59]
	v_mfma_f32_16x16x32_bf16 v[40:43], v[148:151], v[192:195], v[40:43]
	v_mfma_f32_16x16x32_bf16 v[44:47], v[140:143], v[192:195], v[44:47]
	v_mfma_f32_16x16x32_bf16 v[28:31], v[140:143], v[200:203], v[28:31]
	v_mfma_f32_16x16x32_bf16 v[24:27], v[148:151], v[200:203], v[24:27]
	v_mfma_f32_16x16x32_bf16 v[8:11], v[148:151], v[208:211], v[8:11]
	v_mfma_f32_16x16x32_bf16 v[12:15], v[140:143], v[208:211], v[12:15]
	v_mfma_f32_16x16x32_bf16 v[60:63], v[144:147], v[188:191], v[60:63]
	v_mfma_f32_16x16x32_bf16 v[56:59], v[152:155], v[188:191], v[56:59]
	v_mfma_f32_16x16x32_bf16 v[40:43], v[152:155], v[196:199], v[40:43]
	v_mfma_f32_16x16x32_bf16 v[44:47], v[144:147], v[196:199], v[44:47]
	v_mfma_f32_16x16x32_bf16 v[28:31], v[144:147], v[204:207], v[28:31]
	v_mfma_f32_16x16x32_bf16 v[24:27], v[152:155], v[204:207], v[24:27]
	v_mfma_f32_16x16x32_bf16 v[8:11], v[152:155], v[212:215], v[8:11]
	v_mfma_f32_16x16x32_bf16 v[12:15], v[144:147], v[212:215], v[12:15]
	v_mfma_f32_16x16x32_bf16 v[52:55], v[156:159], v[184:187], v[52:55]
	v_mfma_f32_16x16x32_bf16 v[48:51], v[176:179], v[184:187], v[48:51]
	v_mfma_f32_16x16x32_bf16 v[32:35], v[176:179], v[192:195], v[32:35]
	v_mfma_f32_16x16x32_bf16 v[36:39], v[156:159], v[192:195], v[36:39]
	v_mfma_f32_16x16x32_bf16 v[20:23], v[156:159], v[200:203], v[20:23]
	v_mfma_f32_16x16x32_bf16 v[16:19], v[176:179], v[200:203], v[16:19]
	v_mfma_f32_16x16x32_bf16 v[0:3], v[176:179], v[208:211], v[0:3]
	v_mfma_f32_16x16x32_bf16 v[4:7], v[156:159], v[208:211], v[4:7]
	v_mfma_f32_16x16x32_bf16 v[52:55], v[172:175], v[188:191], v[52:55]
	v_mfma_f32_16x16x32_bf16 v[48:51], v[180:183], v[188:191], v[48:51]
	v_mfma_f32_16x16x32_bf16 v[32:35], v[180:183], v[196:199], v[32:35]
	v_mfma_f32_16x16x32_bf16 v[36:39], v[172:175], v[196:199], v[36:39]
	v_mfma_f32_16x16x32_bf16 v[20:23], v[172:175], v[204:207], v[20:23]
	v_mfma_f32_16x16x32_bf16 v[16:19], v[180:183], v[204:207], v[16:19]
	v_mfma_f32_16x16x32_bf16 v[0:3], v[180:183], v[212:215], v[0:3]
	v_mfma_f32_16x16x32_bf16 v[4:7], v[172:175], v[212:215], v[4:7]
	s_barrier
	s_add_i32 s52, s52, 2
	s_add_u32 s0, s0, 0x100
	s_addc_u32 s1, s1, 0
	s_add_u32 s50, s50, 0x100
	s_addc_u32 s51, s51, 0
	s_cmpk_gt_u32 s52, 0x55
	s_cbranch_scc0 .LBB0_1449
	s_setprio 0
	s_and_b64 vcc, exec, s[10:11]
	s_cbranch_vccz .LBB0_1452
	s_barrier
